# k-loop heads aligned to 64 bytes (.p2align 6 before the six GEMM k-loop labels)
# baseline (speedup 1.0000x reference)
.LBB0_258:
	s_ashr_i32 s15, s14, 31
	s_lshl_b64 s[16:17], s[14:15], 19
	s_add_u32 s16, s28, s16
	s_addc_u32 s17, s29, s17
	s_and_b64 s[18:19], s[0:1], exec
	s_cselect_b32 s15, s17, s23
	s_cselect_b32 s47, s16, s22
	s_ashr_i32 s13, s12, 31
	s_lshl_b64 s[18:19], s[12:13], 19
	s_add_u32 s18, s30, s18
	s_addc_u32 s19, s31, s19
	s_and_b64 s[26:27], s[0:1], exec
	s_cselect_b32 s13, s19, s25
	s_cselect_b32 s48, s18, s24
	s_add_u32 s22, s22, 0x40080
	s_addc_u32 s23, s23, 0
	s_add_u32 s49, s24, 0x100
	s_addc_u32 s50, s25, 0
	s_mov_b32 s51, -2
	ds_read_b128 v[152:155], v149
	ds_read_b128 v[156:159], v149 offset:1024
	ds_read_b128 v[160:163], v149 offset:2048
	ds_read_b128 v[164:167], v149 offset:3072
	ds_read_b128 v[168:171], v150
	ds_read_b128 v[172:175], v150 offset:1024
	ds_read_b128 v[176:179], v150 offset:2048
	ds_read_b128 v[184:187], v150 offset:3072
	s_add_u32 s24, s22, 0xfffc0080
	s_addc_u32 s25, s23, -1
	s_cmp_eq_u32 s51, 12
	s_cselect_b32 s27, s15, s25
	s_cselect_b32 s26, s47, s24
	s_cselect_b32 s25, s13, s50
	s_cselect_b32 s24, s48, s49
	v_lshl_add_u64 v[144:145], s[22:23], 0, v[136:137]
	s_add_i32 m0, s21, 0xc000
	ds_read_b128 v[188:191], v151
	ds_read_b128 v[192:195], v151 offset:1024
	ds_read_b128 v[196:199], v151 offset:2048
	ds_read_b128 v[200:203], v151 offset:3072
	ds_read_b128 v[204:207], v151 offset:4096
	ds_read_b128 v[208:211], v151 offset:5120
	ds_read_b128 v[212:215], v151 offset:6144
	ds_read_b128 v[216:219], v151 offset:7168
	global_load_lds_dwordx4 v[144:145], off
	v_lshl_add_u64 v[144:145], s[22:23], 0, v[138:139]
	s_add_i32 m0, s21, 0xe000
	s_nop 0
	global_load_lds_dwordx4 v[144:145], off
	s_waitcnt vmcnt(8)
	s_waitcnt lgkmcnt(0)
	s_barrier
	s_setprio 1
	v_mfma_f32_16x16x32_bf16 v[124:127], v[152:155], v[188:191], 0
	v_mfma_f32_16x16x32_bf16 v[120:123], v[160:163], v[188:191], 0
	v_mfma_f32_16x16x32_bf16 v[108:111], v[152:155], v[196:199], 0
	v_mfma_f32_16x16x32_bf16 v[104:107], v[160:163], v[196:199], 0
	v_mfma_f32_16x16x32_bf16 v[92:95], v[152:155], v[204:207], 0
	v_mfma_f32_16x16x32_bf16 v[88:91], v[160:163], v[204:207], 0
	v_mfma_f32_16x16x32_bf16 v[76:79], v[152:155], v[212:215], 0
	v_mfma_f32_16x16x32_bf16 v[72:75], v[160:163], v[212:215], 0
	v_mfma_f32_16x16x32_bf16 v[124:127], v[156:159], v[192:195], v[124:127]
	v_mfma_f32_16x16x32_bf16 v[120:123], v[164:167], v[192:195], v[120:123]
	v_mfma_f32_16x16x32_bf16 v[108:111], v[156:159], v[200:203], v[108:111]
	v_mfma_f32_16x16x32_bf16 v[104:107], v[164:167], v[200:203], v[104:107]
	v_mfma_f32_16x16x32_bf16 v[92:95], v[156:159], v[208:211], v[92:95]
	v_mfma_f32_16x16x32_bf16 v[88:91], v[164:167], v[208:211], v[88:91]
	v_mfma_f32_16x16x32_bf16 v[76:79], v[156:159], v[216:219], v[76:79]
	v_mfma_f32_16x16x32_bf16 v[72:75], v[164:167], v[216:219], v[72:75]
	v_mfma_f32_16x16x32_bf16 v[116:119], v[168:171], v[188:191], 0
	v_mfma_f32_16x16x32_bf16 v[112:115], v[176:179], v[188:191], 0
	v_mfma_f32_16x16x32_bf16 v[100:103], v[168:171], v[196:199], 0
	v_mfma_f32_16x16x32_bf16 v[96:99], v[176:179], v[196:199], 0
	v_mfma_f32_16x16x32_bf16 v[84:87], v[168:171], v[204:207], 0
	v_mfma_f32_16x16x32_bf16 v[80:83], v[176:179], v[204:207], 0
	v_mfma_f32_16x16x32_bf16 v[68:71], v[168:171], v[212:215], 0
	v_mfma_f32_16x16x32_bf16 v[64:67], v[176:179], v[212:215], 0
	v_mfma_f32_16x16x32_bf16 v[116:119], v[172:175], v[192:195], v[116:119]
	v_mfma_f32_16x16x32_bf16 v[112:115], v[184:187], v[192:195], v[112:115]
	v_mfma_f32_16x16x32_bf16 v[100:103], v[172:175], v[200:203], v[100:103]
	v_mfma_f32_16x16x32_bf16 v[96:99], v[184:187], v[200:203], v[96:99]
	v_mfma_f32_16x16x32_bf16 v[84:87], v[172:175], v[208:211], v[84:87]
	v_mfma_f32_16x16x32_bf16 v[80:83], v[184:187], v[208:211], v[80:83]
	v_mfma_f32_16x16x32_bf16 v[68:71], v[172:175], v[216:219], v[68:71]
	v_mfma_f32_16x16x32_bf16 v[64:67], v[184:187], v[216:219], v[64:67]
	s_setprio 0
	s_barrier
	s_add_i32 s52, s43, s34
	v_lshl_add_u64 v[144:145], s[24:25], 0, v[130:131]
	s_mov_b32 m0, s52
	ds_read_b128 v[188:191], v151 offset:16384
	ds_read_b128 v[192:195], v151 offset:17408
	ds_read_b128 v[196:199], v151 offset:18432
	ds_read_b128 v[200:203], v151 offset:19456
	ds_read_b128 v[204:207], v151 offset:20480
	ds_read_b128 v[208:211], v151 offset:21504
	ds_read_b128 v[212:215], v151 offset:22528
	ds_read_b128 v[216:219], v151 offset:23552
	global_load_lds_dwordx4 v[144:145], off
	s_add_i32 m0, s52, 0x2000
	s_add_u32 s52, s24, 0x40000
	v_lshl_add_u64 v[180:181], s[24:25], 0, v[134:135]
	s_addc_u32 s53, s25, 0
	s_add_i32 s54, s44, s34
	global_load_lds_dwordx4 v[180:181], off
	v_lshl_add_u64 v[220:221], s[52:53], 0, v[130:131]
	s_mov_b32 m0, s54
	v_lshl_add_u64 v[222:223], s[26:27], 0, v[132:133]
	global_load_lds_dwordx4 v[220:221], off
	v_lshl_add_u64 v[220:221], s[52:53], 0, v[134:135]
	s_add_i32 m0, s54, 0x2000
	s_nop 0
	global_load_lds_dwordx4 v[220:221], off
	v_lshl_add_u64 v[220:221], s[26:27], 0, v[128:129]
	s_mov_b32 m0, s21
	s_nop 0
	global_load_lds_dwordx4 v[220:221], off
	s_mov_b32 m0, s36
	s_nop 0
	global_load_lds_dwordx4 v[222:223], off
	s_waitcnt vmcnt(8)
	s_waitcnt lgkmcnt(0)
	s_barrier
	s_setprio 1
	v_mfma_f32_16x16x32_bf16 v[60:63], v[152:155], v[188:191], 0
	v_mfma_f32_16x16x32_bf16 v[56:59], v[160:163], v[188:191], 0
	v_mfma_f32_16x16x32_bf16 v[44:47], v[152:155], v[196:199], 0
	v_mfma_f32_16x16x32_bf16 v[40:43], v[160:163], v[196:199], 0
	v_mfma_f32_16x16x32_bf16 v[28:31], v[152:155], v[204:207], 0
	v_mfma_f32_16x16x32_bf16 v[24:27], v[160:163], v[204:207], 0
	v_mfma_f32_16x16x32_bf16 v[12:15], v[152:155], v[212:215], 0
	v_mfma_f32_16x16x32_bf16 v[8:11], v[160:163], v[212:215], 0
	v_mfma_f32_16x16x32_bf16 v[60:63], v[156:159], v[192:195], v[60:63]
	v_mfma_f32_16x16x32_bf16 v[56:59], v[164:167], v[192:195], v[56:59]
	v_mfma_f32_16x16x32_bf16 v[44:47], v[156:159], v[200:203], v[44:47]
	v_mfma_f32_16x16x32_bf16 v[40:43], v[164:167], v[200:203], v[40:43]
	v_mfma_f32_16x16x32_bf16 v[28:31], v[156:159], v[208:211], v[28:31]
	v_mfma_f32_16x16x32_bf16 v[24:27], v[164:167], v[208:211], v[24:27]
	v_mfma_f32_16x16x32_bf16 v[12:15], v[156:159], v[216:219], v[12:15]
	v_mfma_f32_16x16x32_bf16 v[8:11], v[164:167], v[216:219], v[8:11]
	v_mfma_f32_16x16x32_bf16 v[52:55], v[168:171], v[188:191], 0
	v_mfma_f32_16x16x32_bf16 v[48:51], v[176:179], v[188:191], 0
	v_mfma_f32_16x16x32_bf16 v[36:39], v[168:171], v[196:199], 0
	v_mfma_f32_16x16x32_bf16 v[32:35], v[176:179], v[196:199], 0
	v_mfma_f32_16x16x32_bf16 v[20:23], v[168:171], v[204:207], 0
	v_mfma_f32_16x16x32_bf16 v[16:19], v[176:179], v[204:207], 0
	v_mfma_f32_16x16x32_bf16 v[4:7], v[168:171], v[212:215], 0
	v_mfma_f32_16x16x32_bf16 v[0:3], v[176:179], v[212:215], 0
	v_mfma_f32_16x16x32_bf16 v[52:55], v[172:175], v[192:195], v[52:55]
	v_mfma_f32_16x16x32_bf16 v[48:51], v[184:187], v[192:195], v[48:51]
	v_mfma_f32_16x16x32_bf16 v[36:39], v[172:175], v[200:203], v[36:39]
	v_mfma_f32_16x16x32_bf16 v[32:35], v[184:187], v[200:203], v[32:35]
	v_mfma_f32_16x16x32_bf16 v[20:23], v[172:175], v[208:211], v[20:23]
	v_mfma_f32_16x16x32_bf16 v[16:19], v[184:187], v[208:211], v[16:19]
	v_mfma_f32_16x16x32_bf16 v[4:7], v[172:175], v[216:219], v[4:7]
	v_mfma_f32_16x16x32_bf16 v[0:3], v[184:187], v[216:219], v[0:3]
	s_setprio 0
	s_barrier
	s_add_i32 s52, 0, 0x18000
	s_add_i32 s53, 0, 0x1c000
	v_add_u32_e32 v164, s52, v147
	v_add_u32_e32 v183, s53, v147
	ds_read_b128 v[152:155], v164
	ds_read_b128 v[156:159], v164 offset:1024
	ds_read_b128 v[160:163], v164 offset:2048
	ds_read_b128 v[164:167], v164 offset:3072
	ds_read_b128 v[168:171], v183
	ds_read_b128 v[172:175], v183 offset:1024
	ds_read_b128 v[176:179], v183 offset:2048
	ds_read_b128 v[184:187], v183 offset:3072
	s_add_u32 s26, s26, 0x40000
	s_addc_u32 s27, s27, 0
	s_mov_b32 m0, s37
	v_lshl_add_u64 v[224:225], s[26:27], 0, v[128:129]
	ds_read_b128 v[188:191], v151 offset:32768
	ds_read_b128 v[192:195], v151 offset:33792
	ds_read_b128 v[196:199], v151 offset:34816
	ds_read_b128 v[200:203], v151 offset:35840
	ds_read_b128 v[204:207], v151 offset:36864
	ds_read_b128 v[208:211], v151 offset:37888
	ds_read_b128 v[212:215], v151 offset:38912
	ds_read_b128 v[216:219], v151 offset:39936
	global_load_lds_dwordx4 v[224:225], off
	v_lshl_add_u64 v[224:225], s[26:27], 0, v[132:133]
	s_mov_b32 m0, s38
	s_nop 0
	global_load_lds_dwordx4 v[224:225], off
	s_waitcnt vmcnt(8)
	s_waitcnt lgkmcnt(0)
	s_barrier
	s_setprio 1
	v_mfma_f32_16x16x32_bf16 v[124:127], v[152:155], v[188:191], v[124:127]
	v_mfma_f32_16x16x32_bf16 v[120:123], v[160:163], v[188:191], v[120:123]
	v_mfma_f32_16x16x32_bf16 v[108:111], v[152:155], v[196:199], v[108:111]
	v_mfma_f32_16x16x32_bf16 v[104:107], v[160:163], v[196:199], v[104:107]
	v_mfma_f32_16x16x32_bf16 v[92:95], v[152:155], v[204:207], v[92:95]
	v_mfma_f32_16x16x32_bf16 v[88:91], v[160:163], v[204:207], v[88:91]
	v_mfma_f32_16x16x32_bf16 v[76:79], v[152:155], v[212:215], v[76:79]
	v_mfma_f32_16x16x32_bf16 v[72:75], v[160:163], v[212:215], v[72:75]
	v_mfma_f32_16x16x32_bf16 v[124:127], v[156:159], v[192:195], v[124:127]
	v_mfma_f32_16x16x32_bf16 v[120:123], v[164:167], v[192:195], v[120:123]
	v_mfma_f32_16x16x32_bf16 v[108:111], v[156:159], v[200:203], v[108:111]
	v_mfma_f32_16x16x32_bf16 v[104:107], v[164:167], v[200:203], v[104:107]
	v_mfma_f32_16x16x32_bf16 v[92:95], v[156:159], v[208:211], v[92:95]
	v_mfma_f32_16x16x32_bf16 v[88:91], v[164:167], v[208:211], v[88:91]
	v_mfma_f32_16x16x32_bf16 v[76:79], v[156:159], v[216:219], v[76:79]
	v_mfma_f32_16x16x32_bf16 v[72:75], v[164:167], v[216:219], v[72:75]
	v_mfma_f32_16x16x32_bf16 v[116:119], v[168:171], v[188:191], v[116:119]
	v_mfma_f32_16x16x32_bf16 v[112:115], v[176:179], v[188:191], v[112:115]
	v_mfma_f32_16x16x32_bf16 v[100:103], v[168:171], v[196:199], v[100:103]
	v_mfma_f32_16x16x32_bf16 v[96:99], v[176:179], v[196:199], v[96:99]
	v_mfma_f32_16x16x32_bf16 v[84:87], v[168:171], v[204:207], v[84:87]
	v_mfma_f32_16x16x32_bf16 v[80:83], v[176:179], v[204:207], v[80:83]
	v_mfma_f32_16x16x32_bf16 v[68:71], v[168:171], v[212:215], v[68:71]
	v_mfma_f32_16x16x32_bf16 v[64:67], v[176:179], v[212:215], v[64:67]
	v_mfma_f32_16x16x32_bf16 v[116:119], v[172:175], v[192:195], v[116:119]
	v_mfma_f32_16x16x32_bf16 v[112:115], v[184:187], v[192:195], v[112:115]
	v_mfma_f32_16x16x32_bf16 v[100:103], v[172:175], v[200:203], v[100:103]
	v_mfma_f32_16x16x32_bf16 v[96:99], v[184:187], v[200:203], v[96:99]
	v_mfma_f32_16x16x32_bf16 v[84:87], v[172:175], v[208:211], v[84:87]
	v_mfma_f32_16x16x32_bf16 v[80:83], v[184:187], v[208:211], v[80:83]
	v_mfma_f32_16x16x32_bf16 v[68:71], v[172:175], v[216:219], v[68:71]
	v_mfma_f32_16x16x32_bf16 v[64:67], v[184:187], v[216:219], v[64:67]
	s_setprio 0
	s_barrier
	s_add_i32 s26, s52, s34
	v_lshl_add_u64 v[144:145], v[144:145], 0, s[8:9]
	s_mov_b32 m0, s26
	ds_read_b128 v[188:191], v151 offset:49152
	ds_read_b128 v[192:195], v151 offset:50176
	ds_read_b128 v[196:199], v151 offset:51200
	ds_read_b128 v[200:203], v151 offset:52224
	ds_read_b128 v[204:207], v151 offset:53248
	ds_read_b128 v[208:211], v151 offset:54272
	ds_read_b128 v[212:215], v151 offset:55296
	ds_read_b128 v[216:219], v151 offset:56320
	global_load_lds_dwordx4 v[144:145], off
	s_add_i32 m0, s26, 0x2000
	s_add_u32 s24, s24, 0x40080
	v_lshl_add_u64 v[144:145], v[180:181], 0, s[8:9]
	s_addc_u32 s25, s25, 0
	s_add_i32 s26, s53, s34
	global_load_lds_dwordx4 v[144:145], off
	v_lshl_add_u64 v[144:145], s[24:25], 0, v[130:131]
	s_mov_b32 m0, s26
	s_nop 0
	global_load_lds_dwordx4 v[144:145], off
	v_lshl_add_u64 v[144:145], s[24:25], 0, v[134:135]
	s_add_i32 m0, s26, 0x2000
	s_nop 0
	global_load_lds_dwordx4 v[144:145], off
	v_lshl_add_u64 v[144:145], v[220:221], 0, s[8:9]
	s_mov_b32 m0, s41
	s_nop 0
	global_load_lds_dwordx4 v[144:145], off
	v_lshl_add_u64 v[144:145], v[222:223], 0, s[8:9]
	s_mov_b32 m0, s42
	s_nop 0
	global_load_lds_dwordx4 v[144:145], off
	s_waitcnt vmcnt(8)
	s_waitcnt lgkmcnt(0)
	s_barrier
	s_setprio 1
	v_mfma_f32_16x16x32_bf16 v[60:63], v[152:155], v[188:191], v[60:63]
	v_mfma_f32_16x16x32_bf16 v[56:59], v[160:163], v[188:191], v[56:59]
	v_mfma_f32_16x16x32_bf16 v[44:47], v[152:155], v[196:199], v[44:47]
	v_mfma_f32_16x16x32_bf16 v[40:43], v[160:163], v[196:199], v[40:43]
	v_mfma_f32_16x16x32_bf16 v[28:31], v[152:155], v[204:207], v[28:31]
	v_mfma_f32_16x16x32_bf16 v[24:27], v[160:163], v[204:207], v[24:27]
	v_mfma_f32_16x16x32_bf16 v[12:15], v[152:155], v[212:215], v[12:15]
	v_mfma_f32_16x16x32_bf16 v[8:11], v[160:163], v[212:215], v[8:11]
	v_mfma_f32_16x16x32_bf16 v[60:63], v[156:159], v[192:195], v[60:63]
	v_mfma_f32_16x16x32_bf16 v[56:59], v[164:167], v[192:195], v[56:59]
	v_mfma_f32_16x16x32_bf16 v[44:47], v[156:159], v[200:203], v[44:47]
	v_mfma_f32_16x16x32_bf16 v[40:43], v[164:167], v[200:203], v[40:43]
	v_mfma_f32_16x16x32_bf16 v[28:31], v[156:159], v[208:211], v[28:31]
	v_mfma_f32_16x16x32_bf16 v[24:27], v[164:167], v[208:211], v[24:27]
	v_mfma_f32_16x16x32_bf16 v[12:15], v[156:159], v[216:219], v[12:15]
	v_mfma_f32_16x16x32_bf16 v[8:11], v[164:167], v[216:219], v[8:11]
	v_mfma_f32_16x16x32_bf16 v[52:55], v[168:171], v[188:191], v[52:55]
	v_mfma_f32_16x16x32_bf16 v[48:51], v[176:179], v[188:191], v[48:51]
	v_mfma_f32_16x16x32_bf16 v[36:39], v[168:171], v[196:199], v[36:39]
	v_mfma_f32_16x16x32_bf16 v[32:35], v[176:179], v[196:199], v[32:35]
	v_mfma_f32_16x16x32_bf16 v[20:23], v[168:171], v[204:207], v[20:23]
	v_mfma_f32_16x16x32_bf16 v[16:19], v[176:179], v[204:207], v[16:19]
	v_mfma_f32_16x16x32_bf16 v[4:7], v[168:171], v[212:215], v[4:7]
	v_mfma_f32_16x16x32_bf16 v[0:3], v[176:179], v[212:215], v[0:3]
	v_mfma_f32_16x16x32_bf16 v[52:55], v[172:175], v[192:195], v[52:55]
	v_mfma_f32_16x16x32_bf16 v[48:51], v[184:187], v[192:195], v[48:51]
	v_mfma_f32_16x16x32_bf16 v[36:39], v[172:175], v[200:203], v[36:39]
	v_mfma_f32_16x16x32_bf16 v[32:35], v[184:187], v[200:203], v[32:35]
	v_mfma_f32_16x16x32_bf16 v[20:23], v[172:175], v[208:211], v[20:23]
	v_mfma_f32_16x16x32_bf16 v[16:19], v[184:187], v[208:211], v[16:19]
	v_mfma_f32_16x16x32_bf16 v[4:7], v[172:175], v[216:219], v[4:7]
	v_mfma_f32_16x16x32_bf16 v[0:3], v[184:187], v[216:219], v[0:3]
	s_setprio 0
	s_barrier
	s_add_i32 s51, s51, 2
	s_add_u32 s22, s22, 0x100
	s_addc_u32 s23, s23, 0
	s_add_u32 s49, s49, 0x100
	s_addc_u32 s50, s50, 0
	.p2align	6

.LBB0_337:
	s_add_u32 s24, s24, 0xb0080
	s_addc_u32 s25, s25, 0
	s_add_u32 s55, s26, 0x100
	s_addc_u32 s56, s27, 0
	s_mov_b32 s57, -2
	ds_read_b128 v[150:153], v147
	ds_read_b128 v[154:157], v147 offset:1024
	ds_read_b128 v[158:161], v147 offset:2048
	ds_read_b128 v[162:165], v147 offset:3072
	ds_read_b128 v[166:169], v148
	ds_read_b128 v[170:173], v148 offset:1024
	ds_read_b128 v[174:177], v148 offset:2048
	ds_read_b128 v[178:181], v148 offset:3072
	s_add_u32 s26, s24, 0xfff50080
	s_addc_u32 s27, s25, -1
	s_cmp_eq_u32 s57, 40
	s_cselect_b32 s29, s5, s27
	s_cselect_b32 s28, s4, s26
	s_cselect_b32 s27, s23, s56
	s_cselect_b32 s26, s22, s55
	v_lshl_add_u64 v[216:217], s[24:25], 0, v[136:137]
	s_add_i32 m0, s37, 0xc000
	ds_read_b128 v[184:187], v149
	ds_read_b128 v[188:191], v149 offset:1024
	ds_read_b128 v[192:195], v149 offset:2048
	ds_read_b128 v[196:199], v149 offset:3072
	ds_read_b128 v[200:203], v149 offset:4096
	ds_read_b128 v[204:207], v149 offset:5120
	ds_read_b128 v[208:211], v149 offset:6144
	ds_read_b128 v[212:215], v149 offset:7168
	global_load_lds_dwordx4 v[216:217], off
	v_lshl_add_u64 v[216:217], s[24:25], 0, v[138:139]
	s_add_i32 m0, s37, 0xe000
	s_nop 0
	global_load_lds_dwordx4 v[216:217], off
	s_waitcnt vmcnt(8)
	s_waitcnt lgkmcnt(0)
	s_barrier
	s_setprio 1
	v_mfma_f32_16x16x32_bf16 v[124:127], v[150:153], v[184:187], 0
	v_mfma_f32_16x16x32_bf16 v[120:123], v[158:161], v[184:187], 0
	v_mfma_f32_16x16x32_bf16 v[116:119], v[150:153], v[192:195], 0
	v_mfma_f32_16x16x32_bf16 v[112:115], v[158:161], v[192:195], 0
	v_mfma_f32_16x16x32_bf16 v[100:103], v[150:153], v[200:203], 0
	v_mfma_f32_16x16x32_bf16 v[96:99], v[158:161], v[200:203], 0
	v_mfma_f32_16x16x32_bf16 v[84:87], v[150:153], v[208:211], 0
	v_mfma_f32_16x16x32_bf16 v[80:83], v[158:161], v[208:211], 0
	v_mfma_f32_16x16x32_bf16 v[124:127], v[154:157], v[188:191], v[124:127]
	v_mfma_f32_16x16x32_bf16 v[120:123], v[162:165], v[188:191], v[120:123]
	v_mfma_f32_16x16x32_bf16 v[116:119], v[154:157], v[196:199], v[116:119]
	v_mfma_f32_16x16x32_bf16 v[112:115], v[162:165], v[196:199], v[112:115]
	v_mfma_f32_16x16x32_bf16 v[100:103], v[154:157], v[204:207], v[100:103]
	v_mfma_f32_16x16x32_bf16 v[96:99], v[162:165], v[204:207], v[96:99]
	v_mfma_f32_16x16x32_bf16 v[84:87], v[154:157], v[212:215], v[84:87]
	v_mfma_f32_16x16x32_bf16 v[80:83], v[162:165], v[212:215], v[80:83]
	v_mfma_f32_16x16x32_bf16 v[108:111], v[166:169], v[184:187], 0
	v_mfma_f32_16x16x32_bf16 v[104:107], v[174:177], v[184:187], 0
	v_mfma_f32_16x16x32_bf16 v[92:95], v[166:169], v[192:195], 0
	v_mfma_f32_16x16x32_bf16 v[88:91], v[174:177], v[192:195], 0
	v_mfma_f32_16x16x32_bf16 v[76:79], v[166:169], v[200:203], 0
	v_mfma_f32_16x16x32_bf16 v[72:75], v[174:177], v[200:203], 0
	v_mfma_f32_16x16x32_bf16 v[68:71], v[166:169], v[208:211], 0
	v_mfma_f32_16x16x32_bf16 v[64:67], v[174:177], v[208:211], 0
	v_mfma_f32_16x16x32_bf16 v[108:111], v[170:173], v[188:191], v[108:111]
	v_mfma_f32_16x16x32_bf16 v[104:107], v[178:181], v[188:191], v[104:107]
	v_mfma_f32_16x16x32_bf16 v[92:95], v[170:173], v[196:199], v[92:95]
	v_mfma_f32_16x16x32_bf16 v[88:91], v[178:181], v[196:199], v[88:91]
	v_mfma_f32_16x16x32_bf16 v[76:79], v[170:173], v[204:207], v[76:79]
	v_mfma_f32_16x16x32_bf16 v[72:75], v[178:181], v[204:207], v[72:75]
	v_mfma_f32_16x16x32_bf16 v[68:71], v[170:173], v[212:215], v[68:71]
	v_mfma_f32_16x16x32_bf16 v[64:67], v[178:181], v[212:215], v[64:67]
	s_setprio 0
	s_barrier
	s_add_i32 s58, s45, s36
	v_lshl_add_u64 v[216:217], s[26:27], 0, v[130:131]
	s_mov_b32 m0, s58
	ds_read_b128 v[184:187], v149 offset:16384
	ds_read_b128 v[188:191], v149 offset:17408
	ds_read_b128 v[192:195], v149 offset:18432
	ds_read_b128 v[196:199], v149 offset:19456
	ds_read_b128 v[200:203], v149 offset:20480
	ds_read_b128 v[204:207], v149 offset:21504
	ds_read_b128 v[208:211], v149 offset:22528
	ds_read_b128 v[212:215], v149 offset:23552
	global_load_lds_dwordx4 v[216:217], off
	s_add_i32 m0, s58, 0x2000
	s_add_u32 s58, s26, 0xb0000
	v_lshl_add_u64 v[218:219], s[26:27], 0, v[134:135]
	s_addc_u32 s59, s27, 0
	s_add_i32 s60, s46, s36
	global_load_lds_dwordx4 v[218:219], off
	v_lshl_add_u64 v[220:221], s[58:59], 0, v[130:131]
	s_mov_b32 m0, s60
	v_lshl_add_u64 v[222:223], s[28:29], 0, v[132:133]
	global_load_lds_dwordx4 v[220:221], off
	v_lshl_add_u64 v[220:221], s[58:59], 0, v[134:135]
	s_add_i32 m0, s60, 0x2000
	s_nop 0
	global_load_lds_dwordx4 v[220:221], off
	v_lshl_add_u64 v[220:221], s[28:29], 0, v[128:129]
	s_mov_b32 m0, s37
	s_nop 0
	global_load_lds_dwordx4 v[220:221], off
	s_mov_b32 m0, s38
	s_nop 0
	global_load_lds_dwordx4 v[222:223], off
	s_waitcnt vmcnt(8)
	s_waitcnt lgkmcnt(0)
	s_barrier
	s_setprio 1
	v_mfma_f32_16x16x32_bf16 v[60:63], v[150:153], v[184:187], 0
	v_mfma_f32_16x16x32_bf16 v[56:59], v[158:161], v[184:187], 0
	v_mfma_f32_16x16x32_bf16 v[52:55], v[150:153], v[192:195], 0
	v_mfma_f32_16x16x32_bf16 v[48:51], v[158:161], v[192:195], 0
	v_mfma_f32_16x16x32_bf16 v[36:39], v[150:153], v[200:203], 0
	v_mfma_f32_16x16x32_bf16 v[32:35], v[158:161], v[200:203], 0
	v_mfma_f32_16x16x32_bf16 v[20:23], v[150:153], v[208:211], 0
	v_mfma_f32_16x16x32_bf16 v[16:19], v[158:161], v[208:211], 0
	v_mfma_f32_16x16x32_bf16 v[60:63], v[154:157], v[188:191], v[60:63]
	v_mfma_f32_16x16x32_bf16 v[56:59], v[162:165], v[188:191], v[56:59]
	v_mfma_f32_16x16x32_bf16 v[52:55], v[154:157], v[196:199], v[52:55]
	v_mfma_f32_16x16x32_bf16 v[48:51], v[162:165], v[196:199], v[48:51]
	v_mfma_f32_16x16x32_bf16 v[36:39], v[154:157], v[204:207], v[36:39]
	v_mfma_f32_16x16x32_bf16 v[32:35], v[162:165], v[204:207], v[32:35]
	v_mfma_f32_16x16x32_bf16 v[20:23], v[154:157], v[212:215], v[20:23]
	v_mfma_f32_16x16x32_bf16 v[16:19], v[162:165], v[212:215], v[16:19]
	v_mfma_f32_16x16x32_bf16 v[44:47], v[166:169], v[184:187], 0
	v_mfma_f32_16x16x32_bf16 v[40:43], v[174:177], v[184:187], 0
	v_mfma_f32_16x16x32_bf16 v[28:31], v[166:169], v[192:195], 0
	v_mfma_f32_16x16x32_bf16 v[24:27], v[174:177], v[192:195], 0
	v_mfma_f32_16x16x32_bf16 v[12:15], v[166:169], v[200:203], 0
	v_mfma_f32_16x16x32_bf16 v[8:11], v[174:177], v[200:203], 0
	v_mfma_f32_16x16x32_bf16 v[4:7], v[166:169], v[208:211], 0
	v_mfma_f32_16x16x32_bf16 v[0:3], v[174:177], v[208:211], 0
	v_mfma_f32_16x16x32_bf16 v[44:47], v[170:173], v[188:191], v[44:47]
	v_mfma_f32_16x16x32_bf16 v[40:43], v[178:181], v[188:191], v[40:43]
	v_mfma_f32_16x16x32_bf16 v[28:31], v[170:173], v[196:199], v[28:31]
	v_mfma_f32_16x16x32_bf16 v[24:27], v[178:181], v[196:199], v[24:27]
	v_mfma_f32_16x16x32_bf16 v[12:15], v[170:173], v[204:207], v[12:15]
	v_mfma_f32_16x16x32_bf16 v[8:11], v[178:181], v[204:207], v[8:11]
	v_mfma_f32_16x16x32_bf16 v[4:7], v[170:173], v[212:215], v[4:7]
	v_mfma_f32_16x16x32_bf16 v[0:3], v[178:181], v[212:215], v[0:3]
	s_setprio 0
	s_barrier
	s_add_i32 s58, 0, 0x18000
	s_add_i32 s59, 0, 0x1c000
	v_add_u32_e32 v162, s58, v145
	v_add_u32_e32 v178, s59, v145
	ds_read_b128 v[150:153], v162
	ds_read_b128 v[154:157], v162 offset:1024
	ds_read_b128 v[158:161], v162 offset:2048
	ds_read_b128 v[162:165], v162 offset:3072
	ds_read_b128 v[166:169], v178
	ds_read_b128 v[170:173], v178 offset:1024
	ds_read_b128 v[174:177], v178 offset:2048
	ds_read_b128 v[178:181], v178 offset:3072
	s_add_u32 s28, s28, 0xb0000
	s_addc_u32 s29, s29, 0
	s_mov_b32 m0, s39
	v_lshl_add_u64 v[224:225], s[28:29], 0, v[128:129]
	ds_read_b128 v[184:187], v149 offset:32768
	ds_read_b128 v[188:191], v149 offset:33792
	ds_read_b128 v[192:195], v149 offset:34816
	ds_read_b128 v[196:199], v149 offset:35840
	ds_read_b128 v[200:203], v149 offset:36864
	ds_read_b128 v[204:207], v149 offset:37888
	ds_read_b128 v[208:211], v149 offset:38912
	ds_read_b128 v[212:215], v149 offset:39936
	global_load_lds_dwordx4 v[224:225], off
	v_lshl_add_u64 v[224:225], s[28:29], 0, v[132:133]
	s_mov_b32 m0, s40
	s_nop 0
	global_load_lds_dwordx4 v[224:225], off
	s_waitcnt vmcnt(8)
	s_waitcnt lgkmcnt(0)
	s_barrier
	s_setprio 1
	v_mfma_f32_16x16x32_bf16 v[124:127], v[150:153], v[184:187], v[124:127]
	v_mfma_f32_16x16x32_bf16 v[120:123], v[158:161], v[184:187], v[120:123]
	v_mfma_f32_16x16x32_bf16 v[116:119], v[150:153], v[192:195], v[116:119]
	v_mfma_f32_16x16x32_bf16 v[112:115], v[158:161], v[192:195], v[112:115]
	v_mfma_f32_16x16x32_bf16 v[100:103], v[150:153], v[200:203], v[100:103]
	v_mfma_f32_16x16x32_bf16 v[96:99], v[158:161], v[200:203], v[96:99]
	v_mfma_f32_16x16x32_bf16 v[84:87], v[150:153], v[208:211], v[84:87]
	v_mfma_f32_16x16x32_bf16 v[80:83], v[158:161], v[208:211], v[80:83]
	v_mfma_f32_16x16x32_bf16 v[124:127], v[154:157], v[188:191], v[124:127]
	v_mfma_f32_16x16x32_bf16 v[120:123], v[162:165], v[188:191], v[120:123]
	v_mfma_f32_16x16x32_bf16 v[116:119], v[154:157], v[196:199], v[116:119]
	v_mfma_f32_16x16x32_bf16 v[112:115], v[162:165], v[196:199], v[112:115]
	v_mfma_f32_16x16x32_bf16 v[100:103], v[154:157], v[204:207], v[100:103]
	v_mfma_f32_16x16x32_bf16 v[96:99], v[162:165], v[204:207], v[96:99]
	v_mfma_f32_16x16x32_bf16 v[84:87], v[154:157], v[212:215], v[84:87]
	v_mfma_f32_16x16x32_bf16 v[80:83], v[162:165], v[212:215], v[80:83]
	v_mfma_f32_16x16x32_bf16 v[108:111], v[166:169], v[184:187], v[108:111]
	v_mfma_f32_16x16x32_bf16 v[104:107], v[174:177], v[184:187], v[104:107]
	v_mfma_f32_16x16x32_bf16 v[92:95], v[166:169], v[192:195], v[92:95]
	v_mfma_f32_16x16x32_bf16 v[88:91], v[174:177], v[192:195], v[88:91]
	v_mfma_f32_16x16x32_bf16 v[76:79], v[166:169], v[200:203], v[76:79]
	v_mfma_f32_16x16x32_bf16 v[72:75], v[174:177], v[200:203], v[72:75]
	v_mfma_f32_16x16x32_bf16 v[68:71], v[166:169], v[208:211], v[68:71]
	v_mfma_f32_16x16x32_bf16 v[64:67], v[174:177], v[208:211], v[64:67]
	v_mfma_f32_16x16x32_bf16 v[108:111], v[170:173], v[188:191], v[108:111]
	v_mfma_f32_16x16x32_bf16 v[104:107], v[178:181], v[188:191], v[104:107]
	v_mfma_f32_16x16x32_bf16 v[92:95], v[170:173], v[196:199], v[92:95]
	v_mfma_f32_16x16x32_bf16 v[88:91], v[178:181], v[196:199], v[88:91]
	v_mfma_f32_16x16x32_bf16 v[76:79], v[170:173], v[204:207], v[76:79]
	v_mfma_f32_16x16x32_bf16 v[72:75], v[178:181], v[204:207], v[72:75]
	v_mfma_f32_16x16x32_bf16 v[68:71], v[170:173], v[212:215], v[68:71]
	v_mfma_f32_16x16x32_bf16 v[64:67], v[178:181], v[212:215], v[64:67]
	s_setprio 0
	s_barrier
	s_add_i32 s28, s58, s36
	v_lshl_add_u64 v[216:217], v[216:217], 0, s[10:11]
	s_mov_b32 m0, s28
	ds_read_b128 v[184:187], v149 offset:49152
	ds_read_b128 v[188:191], v149 offset:50176
	ds_read_b128 v[192:195], v149 offset:51200
	ds_read_b128 v[196:199], v149 offset:52224
	ds_read_b128 v[200:203], v149 offset:53248
	ds_read_b128 v[204:207], v149 offset:54272
	ds_read_b128 v[208:211], v149 offset:55296
	ds_read_b128 v[212:215], v149 offset:56320
	global_load_lds_dwordx4 v[216:217], off
	s_add_i32 m0, s28, 0x2000
	s_add_u32 s26, s26, 0xb0080
	v_lshl_add_u64 v[216:217], v[218:219], 0, s[10:11]
	s_addc_u32 s27, s27, 0
	s_add_i32 s28, s59, s36
	global_load_lds_dwordx4 v[216:217], off
	v_lshl_add_u64 v[216:217], s[26:27], 0, v[130:131]
	s_mov_b32 m0, s28
	s_nop 0
	global_load_lds_dwordx4 v[216:217], off
	v_lshl_add_u64 v[216:217], s[26:27], 0, v[134:135]
	s_add_i32 m0, s28, 0x2000
	s_nop 0
	global_load_lds_dwordx4 v[216:217], off
	v_lshl_add_u64 v[216:217], v[220:221], 0, s[10:11]
	s_mov_b32 m0, s43
	s_nop 0
	global_load_lds_dwordx4 v[216:217], off
	v_lshl_add_u64 v[216:217], v[222:223], 0, s[10:11]
	s_mov_b32 m0, s44
	s_nop 0
	global_load_lds_dwordx4 v[216:217], off
	s_waitcnt vmcnt(8)
	s_waitcnt lgkmcnt(0)
	s_barrier
	s_setprio 1
	v_mfma_f32_16x16x32_bf16 v[60:63], v[150:153], v[184:187], v[60:63]
	v_mfma_f32_16x16x32_bf16 v[56:59], v[158:161], v[184:187], v[56:59]
	v_mfma_f32_16x16x32_bf16 v[52:55], v[150:153], v[192:195], v[52:55]
	v_mfma_f32_16x16x32_bf16 v[48:51], v[158:161], v[192:195], v[48:51]
	v_mfma_f32_16x16x32_bf16 v[36:39], v[150:153], v[200:203], v[36:39]
	v_mfma_f32_16x16x32_bf16 v[32:35], v[158:161], v[200:203], v[32:35]
	v_mfma_f32_16x16x32_bf16 v[20:23], v[150:153], v[208:211], v[20:23]
	v_mfma_f32_16x16x32_bf16 v[16:19], v[158:161], v[208:211], v[16:19]
	v_mfma_f32_16x16x32_bf16 v[60:63], v[154:157], v[188:191], v[60:63]
	v_mfma_f32_16x16x32_bf16 v[56:59], v[162:165], v[188:191], v[56:59]
	v_mfma_f32_16x16x32_bf16 v[52:55], v[154:157], v[196:199], v[52:55]
	v_mfma_f32_16x16x32_bf16 v[48:51], v[162:165], v[196:199], v[48:51]
	v_mfma_f32_16x16x32_bf16 v[36:39], v[154:157], v[204:207], v[36:39]
	v_mfma_f32_16x16x32_bf16 v[32:35], v[162:165], v[204:207], v[32:35]
	v_mfma_f32_16x16x32_bf16 v[20:23], v[154:157], v[212:215], v[20:23]
	v_mfma_f32_16x16x32_bf16 v[16:19], v[162:165], v[212:215], v[16:19]
	v_mfma_f32_16x16x32_bf16 v[44:47], v[166:169], v[184:187], v[44:47]
	v_mfma_f32_16x16x32_bf16 v[40:43], v[174:177], v[184:187], v[40:43]
	v_mfma_f32_16x16x32_bf16 v[28:31], v[166:169], v[192:195], v[28:31]
	v_mfma_f32_16x16x32_bf16 v[24:27], v[174:177], v[192:195], v[24:27]
	v_mfma_f32_16x16x32_bf16 v[12:15], v[166:169], v[200:203], v[12:15]
	v_mfma_f32_16x16x32_bf16 v[8:11], v[174:177], v[200:203], v[8:11]
	v_mfma_f32_16x16x32_bf16 v[4:7], v[166:169], v[208:211], v[4:7]
	v_mfma_f32_16x16x32_bf16 v[0:3], v[174:177], v[208:211], v[0:3]
	v_mfma_f32_16x16x32_bf16 v[44:47], v[170:173], v[188:191], v[44:47]
	v_mfma_f32_16x16x32_bf16 v[40:43], v[178:181], v[188:191], v[40:43]
	v_mfma_f32_16x16x32_bf16 v[28:31], v[170:173], v[196:199], v[28:31]
	v_mfma_f32_16x16x32_bf16 v[24:27], v[178:181], v[196:199], v[24:27]
	v_mfma_f32_16x16x32_bf16 v[12:15], v[170:173], v[204:207], v[12:15]
	v_mfma_f32_16x16x32_bf16 v[8:11], v[178:181], v[204:207], v[8:11]
	v_mfma_f32_16x16x32_bf16 v[4:7], v[170:173], v[212:215], v[4:7]
	v_mfma_f32_16x16x32_bf16 v[0:3], v[178:181], v[212:215], v[0:3]
	s_setprio 0
	s_barrier
	s_add_i32 s57, s57, 2
	s_add_u32 s24, s24, 0x100
	s_addc_u32 s25, s25, 0
	s_add_u32 s55, s55, 0x100
	s_addc_u32 s56, s56, 0
	.p2align	6

.LBB0_474:
	s_ashr_i32 s39, s38, 31
	s_lshl_b64 s[40:41], s[38:39], 19
	s_add_u32 s40, s52, s40
	s_addc_u32 s41, s53, s41
	s_and_b64 s[42:43], s[6:7], exec
	s_cselect_b32 s1, s41, s47
	s_cselect_b32 s39, s40, s46
	s_ashr_i32 s37, s36, 31
	s_lshl_b64 s[42:43], s[36:37], 19
	s_add_u32 s42, s54, s42
	s_addc_u32 s43, s55, s43
	s_and_b64 s[50:51], s[6:7], exec
	s_cselect_b32 s37, s43, s49
	s_cselect_b32 s45, s42, s48
	s_add_u32 s46, s46, 0x40080
	s_addc_u32 s47, s47, 0
	s_add_u32 s75, s48, 0x100
	s_addc_u32 s76, s49, 0
	s_mov_b32 s77, -2
	ds_read_b128 v[150:153], v158
	ds_read_b128 v[162:165], v158 offset:1024
	ds_read_b128 v[166:169], v158 offset:2048
	ds_read_b128 v[170:173], v158 offset:3072
	ds_read_b128 v[174:177], v159
	ds_read_b128 v[178:181], v159 offset:1024
	ds_read_b128 v[184:187], v159 offset:2048
	ds_read_b128 v[188:191], v159 offset:3072
	s_add_u32 s48, s46, 0xfffc0080
	s_addc_u32 s49, s47, -1
	s_cmp_eq_u32 s77, 12
	s_cselect_b32 s51, s1, s49
	s_cselect_b32 s50, s39, s48
	s_cselect_b32 s49, s37, s76
	s_cselect_b32 s48, s45, s75
	v_lshl_add_u64 v[224:225], s[46:47], 0, v[142:143]
	s_add_i32 m0, s57, 0xc000
	ds_read_b128 v[192:195], v160
	ds_read_b128 v[196:199], v160 offset:1024
	ds_read_b128 v[200:203], v160 offset:2048
	ds_read_b128 v[204:207], v160 offset:3072
	ds_read_b128 v[208:211], v160 offset:4096
	ds_read_b128 v[212:215], v160 offset:5120
	ds_read_b128 v[216:219], v160 offset:6144
	ds_read_b128 v[220:223], v160 offset:7168
	global_load_lds_dwordx4 v[224:225], off
	v_lshl_add_u64 v[224:225], s[46:47], 0, v[144:145]
	s_add_i32 m0, s57, 0xe000
	s_nop 0
	global_load_lds_dwordx4 v[224:225], off
	s_waitcnt vmcnt(8)
	s_waitcnt lgkmcnt(0)
	s_barrier
	s_setprio 1
	v_mfma_f32_16x16x32_bf16 v[64:67], v[150:153], v[192:195], 0
	v_mfma_f32_16x16x32_bf16 v[28:31], v[166:169], v[192:195], 0
	v_mfma_f32_16x16x32_bf16 v[60:63], v[150:153], v[200:203], 0
	v_mfma_f32_16x16x32_bf16 v[24:27], v[166:169], v[200:203], 0
	v_mfma_f32_16x16x32_bf16 v[56:59], v[150:153], v[208:211], 0
	v_mfma_f32_16x16x32_bf16 v[20:23], v[166:169], v[208:211], 0
	v_mfma_f32_16x16x32_bf16 v[52:55], v[150:153], v[216:219], 0
	v_mfma_f32_16x16x32_bf16 v[16:19], v[166:169], v[216:219], 0
	v_mfma_f32_16x16x32_bf16 v[64:67], v[162:165], v[196:199], v[64:67]
	v_mfma_f32_16x16x32_bf16 v[28:31], v[170:173], v[196:199], v[28:31]
	v_mfma_f32_16x16x32_bf16 v[60:63], v[162:165], v[204:207], v[60:63]
	v_mfma_f32_16x16x32_bf16 v[24:27], v[170:173], v[204:207], v[24:27]
	v_mfma_f32_16x16x32_bf16 v[56:59], v[162:165], v[212:215], v[56:59]
	v_mfma_f32_16x16x32_bf16 v[20:23], v[170:173], v[212:215], v[20:23]
	v_mfma_f32_16x16x32_bf16 v[52:55], v[162:165], v[220:223], v[52:55]
	v_mfma_f32_16x16x32_bf16 v[16:19], v[170:173], v[220:223], v[16:19]
	v_mfma_f32_16x16x32_bf16 v[124:127], v[174:177], v[192:195], 0
	v_mfma_f32_16x16x32_bf16 v[120:123], v[184:187], v[192:195], 0
	v_mfma_f32_16x16x32_bf16 v[116:119], v[174:177], v[200:203], 0
	v_mfma_f32_16x16x32_bf16 v[112:115], v[184:187], v[200:203], 0
	v_mfma_f32_16x16x32_bf16 v[108:111], v[174:177], v[208:211], 0
	v_mfma_f32_16x16x32_bf16 v[104:107], v[184:187], v[208:211], 0
	v_mfma_f32_16x16x32_bf16 v[100:103], v[174:177], v[216:219], 0
	v_mfma_f32_16x16x32_bf16 v[96:99], v[184:187], v[216:219], 0
	v_mfma_f32_16x16x32_bf16 v[124:127], v[178:181], v[196:199], v[124:127]
	v_mfma_f32_16x16x32_bf16 v[120:123], v[188:191], v[196:199], v[120:123]
	v_mfma_f32_16x16x32_bf16 v[116:119], v[178:181], v[204:207], v[116:119]
	v_mfma_f32_16x16x32_bf16 v[112:115], v[188:191], v[204:207], v[112:115]
	v_mfma_f32_16x16x32_bf16 v[108:111], v[178:181], v[212:215], v[108:111]
	v_mfma_f32_16x16x32_bf16 v[104:107], v[188:191], v[212:215], v[104:107]
	v_mfma_f32_16x16x32_bf16 v[100:103], v[178:181], v[220:223], v[100:103]
	v_mfma_f32_16x16x32_bf16 v[96:99], v[188:191], v[220:223], v[96:99]
	s_setprio 0
	s_barrier
	s_add_i32 s78, s66, s56
	v_lshl_add_u64 v[224:225], s[48:49], 0, v[130:131]
	s_mov_b32 m0, s78
	ds_read_b128 v[192:195], v160 offset:16384
	ds_read_b128 v[196:199], v160 offset:17408
	ds_read_b128 v[200:203], v160 offset:18432
	ds_read_b128 v[204:207], v160 offset:19456
	ds_read_b128 v[208:211], v160 offset:20480
	ds_read_b128 v[212:215], v160 offset:21504
	ds_read_b128 v[216:219], v160 offset:22528
	ds_read_b128 v[220:223], v160 offset:23552
	global_load_lds_dwordx4 v[224:225], off
	s_add_i32 m0, s78, 0x2000
	s_add_u32 s78, s48, 0x40000
	v_lshl_add_u64 v[226:227], s[48:49], 0, v[134:135]
	s_addc_u32 s79, s49, 0
	s_add_i32 s80, s67, s56
	global_load_lds_dwordx4 v[226:227], off
	v_lshl_add_u64 v[228:229], s[78:79], 0, v[130:131]
	s_mov_b32 m0, s80
	v_lshl_add_u64 v[230:231], s[50:51], 0, v[132:133]
	global_load_lds_dwordx4 v[228:229], off
	v_lshl_add_u64 v[228:229], s[78:79], 0, v[134:135]
	s_add_i32 m0, s80, 0x2000
	s_nop 0
	global_load_lds_dwordx4 v[228:229], off
	v_lshl_add_u64 v[228:229], s[50:51], 0, v[128:129]
	s_mov_b32 m0, s57
	s_nop 0
	global_load_lds_dwordx4 v[228:229], off
	s_mov_b32 m0, s58
	s_nop 0
	global_load_lds_dwordx4 v[230:231], off
	s_waitcnt vmcnt(8)
	s_waitcnt lgkmcnt(0)
	s_barrier
	s_setprio 1
	v_mfma_f32_16x16x32_bf16 v[44:47], v[150:153], v[192:195], 0
	v_mfma_f32_16x16x32_bf16 v[12:15], v[166:169], v[192:195], 0
	v_mfma_f32_16x16x32_bf16 v[40:43], v[150:153], v[200:203], 0
	v_mfma_f32_16x16x32_bf16 v[8:11], v[166:169], v[200:203], 0
	v_mfma_f32_16x16x32_bf16 v[36:39], v[150:153], v[208:211], 0
	v_mfma_f32_16x16x32_bf16 v[4:7], v[166:169], v[208:211], 0
	v_mfma_f32_16x16x32_bf16 v[32:35], v[150:153], v[216:219], 0
	v_mfma_f32_16x16x32_bf16 v[0:3], v[166:169], v[216:219], 0
	v_mfma_f32_16x16x32_bf16 v[44:47], v[162:165], v[196:199], v[44:47]
	v_mfma_f32_16x16x32_bf16 v[12:15], v[170:173], v[196:199], v[12:15]
	v_mfma_f32_16x16x32_bf16 v[40:43], v[162:165], v[204:207], v[40:43]
	v_mfma_f32_16x16x32_bf16 v[8:11], v[170:173], v[204:207], v[8:11]
	v_mfma_f32_16x16x32_bf16 v[36:39], v[162:165], v[212:215], v[36:39]
	v_mfma_f32_16x16x32_bf16 v[4:7], v[170:173], v[212:215], v[4:7]
	v_mfma_f32_16x16x32_bf16 v[32:35], v[162:165], v[220:223], v[32:35]
	v_mfma_f32_16x16x32_bf16 v[0:3], v[170:173], v[220:223], v[0:3]
	v_mfma_f32_16x16x32_bf16 v[92:95], v[174:177], v[192:195], 0
	v_mfma_f32_16x16x32_bf16 v[88:91], v[184:187], v[192:195], 0
	v_mfma_f32_16x16x32_bf16 v[84:87], v[174:177], v[200:203], 0
	v_mfma_f32_16x16x32_bf16 v[80:83], v[184:187], v[200:203], 0
	v_mfma_f32_16x16x32_bf16 v[76:79], v[174:177], v[208:211], 0
	v_mfma_f32_16x16x32_bf16 v[72:75], v[184:187], v[208:211], 0
	v_mfma_f32_16x16x32_bf16 v[68:71], v[174:177], v[216:219], 0
	v_mfma_f32_16x16x32_bf16 v[48:51], v[184:187], v[216:219], 0
	v_mfma_f32_16x16x32_bf16 v[92:95], v[178:181], v[196:199], v[92:95]
	v_mfma_f32_16x16x32_bf16 v[88:91], v[188:191], v[196:199], v[88:91]
	v_mfma_f32_16x16x32_bf16 v[84:87], v[178:181], v[204:207], v[84:87]
	v_mfma_f32_16x16x32_bf16 v[80:83], v[188:191], v[204:207], v[80:83]
	v_mfma_f32_16x16x32_bf16 v[76:79], v[178:181], v[212:215], v[76:79]
	v_mfma_f32_16x16x32_bf16 v[72:75], v[188:191], v[212:215], v[72:75]
	v_mfma_f32_16x16x32_bf16 v[68:71], v[178:181], v[220:223], v[68:71]
	v_mfma_f32_16x16x32_bf16 v[48:51], v[188:191], v[220:223], v[48:51]
	s_setprio 0
	s_barrier
	s_add_i32 s78, 0, 0x18000
	v_add_u32_e32 v136, s78, v156
	s_add_i32 s79, 0, 0x1c000
	ds_read_b128 v[150:153], v136
	ds_read_b128 v[162:165], v136 offset:1024
	ds_read_b128 v[166:169], v136 offset:2048
	ds_read_b128 v[170:173], v136 offset:3072
	v_add_u32_e32 v136, s79, v156
	ds_read_b128 v[174:177], v136
	ds_read_b128 v[178:181], v136 offset:1024
	ds_read_b128 v[184:187], v136 offset:2048
	ds_read_b128 v[188:191], v136 offset:3072
	s_add_u32 s50, s50, 0x40000
	s_addc_u32 s51, s51, 0
	s_mov_b32 m0, s59
	v_lshl_add_u64 v[232:233], s[50:51], 0, v[128:129]
	ds_read_b128 v[192:195], v160 offset:32768
	ds_read_b128 v[196:199], v160 offset:33792
	ds_read_b128 v[200:203], v160 offset:34816
	ds_read_b128 v[204:207], v160 offset:35840
	ds_read_b128 v[208:211], v160 offset:36864
	ds_read_b128 v[212:215], v160 offset:37888
	ds_read_b128 v[216:219], v160 offset:38912
	ds_read_b128 v[220:223], v160 offset:39936
	global_load_lds_dwordx4 v[232:233], off
	v_lshl_add_u64 v[232:233], s[50:51], 0, v[132:133]
	s_mov_b32 m0, s60
	s_nop 0
	global_load_lds_dwordx4 v[232:233], off
	s_waitcnt vmcnt(8)
	s_waitcnt lgkmcnt(0)
	s_barrier
	s_setprio 1
	v_mfma_f32_16x16x32_bf16 v[64:67], v[150:153], v[192:195], v[64:67]
	v_mfma_f32_16x16x32_bf16 v[28:31], v[166:169], v[192:195], v[28:31]
	v_mfma_f32_16x16x32_bf16 v[60:63], v[150:153], v[200:203], v[60:63]
	v_mfma_f32_16x16x32_bf16 v[24:27], v[166:169], v[200:203], v[24:27]
	v_mfma_f32_16x16x32_bf16 v[56:59], v[150:153], v[208:211], v[56:59]
	v_mfma_f32_16x16x32_bf16 v[20:23], v[166:169], v[208:211], v[20:23]
	v_mfma_f32_16x16x32_bf16 v[52:55], v[150:153], v[216:219], v[52:55]
	v_mfma_f32_16x16x32_bf16 v[16:19], v[166:169], v[216:219], v[16:19]
	v_mfma_f32_16x16x32_bf16 v[64:67], v[162:165], v[196:199], v[64:67]
	v_mfma_f32_16x16x32_bf16 v[28:31], v[170:173], v[196:199], v[28:31]
	v_mfma_f32_16x16x32_bf16 v[60:63], v[162:165], v[204:207], v[60:63]
	v_mfma_f32_16x16x32_bf16 v[24:27], v[170:173], v[204:207], v[24:27]
	v_mfma_f32_16x16x32_bf16 v[56:59], v[162:165], v[212:215], v[56:59]
	v_mfma_f32_16x16x32_bf16 v[20:23], v[170:173], v[212:215], v[20:23]
	v_mfma_f32_16x16x32_bf16 v[52:55], v[162:165], v[220:223], v[52:55]
	v_mfma_f32_16x16x32_bf16 v[16:19], v[170:173], v[220:223], v[16:19]
	v_mfma_f32_16x16x32_bf16 v[124:127], v[174:177], v[192:195], v[124:127]
	v_mfma_f32_16x16x32_bf16 v[120:123], v[184:187], v[192:195], v[120:123]
	v_mfma_f32_16x16x32_bf16 v[116:119], v[174:177], v[200:203], v[116:119]
	v_mfma_f32_16x16x32_bf16 v[112:115], v[184:187], v[200:203], v[112:115]
	v_mfma_f32_16x16x32_bf16 v[108:111], v[174:177], v[208:211], v[108:111]
	v_mfma_f32_16x16x32_bf16 v[104:107], v[184:187], v[208:211], v[104:107]
	v_mfma_f32_16x16x32_bf16 v[100:103], v[174:177], v[216:219], v[100:103]
	v_mfma_f32_16x16x32_bf16 v[96:99], v[184:187], v[216:219], v[96:99]
	v_mfma_f32_16x16x32_bf16 v[124:127], v[178:181], v[196:199], v[124:127]
	v_mfma_f32_16x16x32_bf16 v[120:123], v[188:191], v[196:199], v[120:123]
	v_mfma_f32_16x16x32_bf16 v[116:119], v[178:181], v[204:207], v[116:119]
	v_mfma_f32_16x16x32_bf16 v[112:115], v[188:191], v[204:207], v[112:115]
	v_mfma_f32_16x16x32_bf16 v[108:111], v[178:181], v[212:215], v[108:111]
	v_mfma_f32_16x16x32_bf16 v[104:107], v[188:191], v[212:215], v[104:107]
	v_mfma_f32_16x16x32_bf16 v[100:103], v[178:181], v[220:223], v[100:103]
	v_mfma_f32_16x16x32_bf16 v[96:99], v[188:191], v[220:223], v[96:99]
	s_setprio 0
	s_barrier
	s_add_i32 s50, s78, s56
	v_lshl_add_u64 v[224:225], v[224:225], 0, s[28:29]
	s_mov_b32 m0, s50
	ds_read_b128 v[192:195], v160 offset:49152
	ds_read_b128 v[196:199], v160 offset:50176
	ds_read_b128 v[200:203], v160 offset:51200
	ds_read_b128 v[204:207], v160 offset:52224
	ds_read_b128 v[208:211], v160 offset:53248
	ds_read_b128 v[212:215], v160 offset:54272
	ds_read_b128 v[216:219], v160 offset:55296
	ds_read_b128 v[220:223], v160 offset:56320
	global_load_lds_dwordx4 v[224:225], off
	s_add_i32 m0, s50, 0x2000
	s_add_u32 s48, s48, 0x40080
	v_lshl_add_u64 v[224:225], v[226:227], 0, s[28:29]
	s_addc_u32 s49, s49, 0
	s_add_i32 s50, s79, s56
	global_load_lds_dwordx4 v[224:225], off
	v_lshl_add_u64 v[224:225], s[48:49], 0, v[130:131]
	s_mov_b32 m0, s50
	s_nop 0
	global_load_lds_dwordx4 v[224:225], off
	v_lshl_add_u64 v[224:225], s[48:49], 0, v[134:135]
	s_add_i32 m0, s50, 0x2000
	s_nop 0
	global_load_lds_dwordx4 v[224:225], off
	v_lshl_add_u64 v[224:225], v[228:229], 0, s[28:29]
	s_mov_b32 m0, s63
	s_nop 0
	global_load_lds_dwordx4 v[224:225], off
	v_lshl_add_u64 v[224:225], v[230:231], 0, s[28:29]
	s_mov_b32 m0, s64
	s_nop 0
	global_load_lds_dwordx4 v[224:225], off
	s_waitcnt vmcnt(8)
	s_waitcnt lgkmcnt(0)
	s_barrier
	s_setprio 1
	v_mfma_f32_16x16x32_bf16 v[44:47], v[150:153], v[192:195], v[44:47]
	v_mfma_f32_16x16x32_bf16 v[12:15], v[166:169], v[192:195], v[12:15]
	v_mfma_f32_16x16x32_bf16 v[40:43], v[150:153], v[200:203], v[40:43]
	v_mfma_f32_16x16x32_bf16 v[8:11], v[166:169], v[200:203], v[8:11]
	v_mfma_f32_16x16x32_bf16 v[36:39], v[150:153], v[208:211], v[36:39]
	v_mfma_f32_16x16x32_bf16 v[4:7], v[166:169], v[208:211], v[4:7]
	v_mfma_f32_16x16x32_bf16 v[32:35], v[150:153], v[216:219], v[32:35]
	v_mfma_f32_16x16x32_bf16 v[0:3], v[166:169], v[216:219], v[0:3]
	v_mfma_f32_16x16x32_bf16 v[44:47], v[162:165], v[196:199], v[44:47]
	v_mfma_f32_16x16x32_bf16 v[12:15], v[170:173], v[196:199], v[12:15]
	v_mfma_f32_16x16x32_bf16 v[40:43], v[162:165], v[204:207], v[40:43]
	v_mfma_f32_16x16x32_bf16 v[8:11], v[170:173], v[204:207], v[8:11]
	v_mfma_f32_16x16x32_bf16 v[36:39], v[162:165], v[212:215], v[36:39]
	v_mfma_f32_16x16x32_bf16 v[4:7], v[170:173], v[212:215], v[4:7]
	v_mfma_f32_16x16x32_bf16 v[32:35], v[162:165], v[220:223], v[32:35]
	v_mfma_f32_16x16x32_bf16 v[0:3], v[170:173], v[220:223], v[0:3]
	v_mfma_f32_16x16x32_bf16 v[92:95], v[174:177], v[192:195], v[92:95]
	v_mfma_f32_16x16x32_bf16 v[88:91], v[184:187], v[192:195], v[88:91]
	v_mfma_f32_16x16x32_bf16 v[84:87], v[174:177], v[200:203], v[84:87]
	v_mfma_f32_16x16x32_bf16 v[80:83], v[184:187], v[200:203], v[80:83]
	v_mfma_f32_16x16x32_bf16 v[76:79], v[174:177], v[208:211], v[76:79]
	v_mfma_f32_16x16x32_bf16 v[72:75], v[184:187], v[208:211], v[72:75]
	v_mfma_f32_16x16x32_bf16 v[68:71], v[174:177], v[216:219], v[68:71]
	v_mfma_f32_16x16x32_bf16 v[48:51], v[184:187], v[216:219], v[48:51]
	v_mfma_f32_16x16x32_bf16 v[92:95], v[178:181], v[196:199], v[92:95]
	v_mfma_f32_16x16x32_bf16 v[88:91], v[188:191], v[196:199], v[88:91]
	v_mfma_f32_16x16x32_bf16 v[84:87], v[178:181], v[204:207], v[84:87]
	v_mfma_f32_16x16x32_bf16 v[80:83], v[188:191], v[204:207], v[80:83]
	v_mfma_f32_16x16x32_bf16 v[76:79], v[178:181], v[212:215], v[76:79]
	v_mfma_f32_16x16x32_bf16 v[72:75], v[188:191], v[212:215], v[72:75]
	v_mfma_f32_16x16x32_bf16 v[68:71], v[178:181], v[220:223], v[68:71]
	v_mfma_f32_16x16x32_bf16 v[48:51], v[188:191], v[220:223], v[48:51]
	s_setprio 0
	s_barrier
	s_add_i32 s77, s77, 2
	s_add_u32 s46, s46, 0x100
	s_addc_u32 s47, s47, 0
	s_add_u32 s75, s75, 0x100
	s_addc_u32 s76, s76, 0
	.p2align	6

.LBB0_1273:
	s_ashr_i32 s23, s22, 31
	s_lshl_b64 s[26:27], s[22:23], 20
	s_add_u32 s26, s35, s26
	s_addc_u32 s27, s36, s27
	s_and_b64 s[4:5], s[4:5], exec
	s_cselect_b32 s23, s27, s29
	s_cselect_b32 s56, s26, s28
	s_add_u32 s4, s30, 0x160080
	s_addc_u32 s5, s31, 0
	s_add_u32 s57, s28, 0x100
	s_addc_u32 s58, s29, 0
	s_mov_b32 s59, -2
	s_waitcnt lgkmcnt(0)
	ds_read_b128 v[150:153], v147
	ds_read_b128 v[154:157], v147 offset:1024
	ds_read_b128 v[158:161], v147 offset:2048
	ds_read_b128 v[162:165], v147 offset:3072
	ds_read_b128 v[166:169], v148
	ds_read_b128 v[170:173], v148 offset:1024
	ds_read_b128 v[174:177], v148 offset:2048
	ds_read_b128 v[178:181], v148 offset:3072
	s_add_u32 s28, s4, 0xffea0080
	s_addc_u32 s29, s5, -1
	s_cmp_eq_u32 s59, 28
	s_cselect_b32 s31, s25, s29
	s_cselect_b32 s30, s24, s28
	s_cselect_b32 s29, s23, s58
	s_cselect_b32 s28, s56, s57
	v_lshl_add_u64 v[216:217], s[4:5], 0, v[136:137]
	s_add_i32 m0, s39, 0xc000
	ds_read_b128 v[184:187], v149
	ds_read_b128 v[188:191], v149 offset:1024
	ds_read_b128 v[192:195], v149 offset:2048
	ds_read_b128 v[196:199], v149 offset:3072
	ds_read_b128 v[200:203], v149 offset:4096
	ds_read_b128 v[204:207], v149 offset:5120
	ds_read_b128 v[208:211], v149 offset:6144
	ds_read_b128 v[212:215], v149 offset:7168
	global_load_lds_dwordx4 v[216:217], off
	v_lshl_add_u64 v[216:217], s[4:5], 0, v[138:139]
	s_add_i32 m0, s39, 0xe000
	s_nop 0
	global_load_lds_dwordx4 v[216:217], off
	s_waitcnt vmcnt(8)
	s_waitcnt lgkmcnt(0)
	s_barrier
	s_setprio 1
	v_mfma_f32_16x16x32_bf16 v[124:127], v[150:153], v[184:187], 0
	v_mfma_f32_16x16x32_bf16 v[120:123], v[158:161], v[184:187], 0
	v_mfma_f32_16x16x32_bf16 v[116:119], v[150:153], v[192:195], 0
	v_mfma_f32_16x16x32_bf16 v[112:115], v[158:161], v[192:195], 0
	v_mfma_f32_16x16x32_bf16 v[100:103], v[150:153], v[200:203], 0
	v_mfma_f32_16x16x32_bf16 v[96:99], v[158:161], v[200:203], 0
	v_mfma_f32_16x16x32_bf16 v[84:87], v[150:153], v[208:211], 0
	v_mfma_f32_16x16x32_bf16 v[80:83], v[158:161], v[208:211], 0
	v_mfma_f32_16x16x32_bf16 v[124:127], v[154:157], v[188:191], v[124:127]
	v_mfma_f32_16x16x32_bf16 v[120:123], v[162:165], v[188:191], v[120:123]
	v_mfma_f32_16x16x32_bf16 v[116:119], v[154:157], v[196:199], v[116:119]
	v_mfma_f32_16x16x32_bf16 v[112:115], v[162:165], v[196:199], v[112:115]
	v_mfma_f32_16x16x32_bf16 v[100:103], v[154:157], v[204:207], v[100:103]
	v_mfma_f32_16x16x32_bf16 v[96:99], v[162:165], v[204:207], v[96:99]
	v_mfma_f32_16x16x32_bf16 v[84:87], v[154:157], v[212:215], v[84:87]
	v_mfma_f32_16x16x32_bf16 v[80:83], v[162:165], v[212:215], v[80:83]
	v_mfma_f32_16x16x32_bf16 v[108:111], v[166:169], v[184:187], 0
	v_mfma_f32_16x16x32_bf16 v[104:107], v[174:177], v[184:187], 0
	v_mfma_f32_16x16x32_bf16 v[92:95], v[166:169], v[192:195], 0
	v_mfma_f32_16x16x32_bf16 v[88:91], v[174:177], v[192:195], 0
	v_mfma_f32_16x16x32_bf16 v[76:79], v[166:169], v[200:203], 0
	v_mfma_f32_16x16x32_bf16 v[72:75], v[174:177], v[200:203], 0
	v_mfma_f32_16x16x32_bf16 v[68:71], v[166:169], v[208:211], 0
	v_mfma_f32_16x16x32_bf16 v[64:67], v[174:177], v[208:211], 0
	v_mfma_f32_16x16x32_bf16 v[108:111], v[170:173], v[188:191], v[108:111]
	v_mfma_f32_16x16x32_bf16 v[104:107], v[178:181], v[188:191], v[104:107]
	v_mfma_f32_16x16x32_bf16 v[92:95], v[170:173], v[196:199], v[92:95]
	v_mfma_f32_16x16x32_bf16 v[88:91], v[178:181], v[196:199], v[88:91]
	v_mfma_f32_16x16x32_bf16 v[76:79], v[170:173], v[204:207], v[76:79]
	v_mfma_f32_16x16x32_bf16 v[72:75], v[178:181], v[204:207], v[72:75]
	v_mfma_f32_16x16x32_bf16 v[68:71], v[170:173], v[212:215], v[68:71]
	v_mfma_f32_16x16x32_bf16 v[64:67], v[178:181], v[212:215], v[64:67]
	s_setprio 0
	s_barrier
	s_add_i32 s60, s47, s38
	v_lshl_add_u64 v[216:217], s[28:29], 0, v[130:131]
	s_mov_b32 m0, s60
	ds_read_b128 v[184:187], v149 offset:16384
	ds_read_b128 v[188:191], v149 offset:17408
	ds_read_b128 v[192:195], v149 offset:18432
	ds_read_b128 v[196:199], v149 offset:19456
	ds_read_b128 v[200:203], v149 offset:20480
	ds_read_b128 v[204:207], v149 offset:21504
	ds_read_b128 v[208:211], v149 offset:22528
	ds_read_b128 v[212:215], v149 offset:23552
	global_load_lds_dwordx4 v[216:217], off
	s_add_i32 m0, s60, 0x2000
	s_add_u32 s60, s28, 0x80000
	v_lshl_add_u64 v[218:219], s[28:29], 0, v[134:135]
	s_addc_u32 s61, s29, 0
	s_add_i32 s62, s48, s38
	global_load_lds_dwordx4 v[218:219], off
	v_lshl_add_u64 v[220:221], s[60:61], 0, v[130:131]
	s_mov_b32 m0, s62
	v_lshl_add_u64 v[222:223], s[30:31], 0, v[132:133]
	global_load_lds_dwordx4 v[220:221], off
	v_lshl_add_u64 v[220:221], s[60:61], 0, v[134:135]
	s_add_i32 m0, s62, 0x2000
	s_nop 0
	global_load_lds_dwordx4 v[220:221], off
	v_lshl_add_u64 v[220:221], s[30:31], 0, v[128:129]
	s_mov_b32 m0, s39
	s_nop 0
	global_load_lds_dwordx4 v[220:221], off
	s_mov_b32 m0, s40
	s_nop 0
	global_load_lds_dwordx4 v[222:223], off
	s_waitcnt vmcnt(8)
	s_waitcnt lgkmcnt(0)
	s_barrier
	s_setprio 1
	v_mfma_f32_16x16x32_bf16 v[60:63], v[150:153], v[184:187], 0
	v_mfma_f32_16x16x32_bf16 v[56:59], v[158:161], v[184:187], 0
	v_mfma_f32_16x16x32_bf16 v[52:55], v[150:153], v[192:195], 0
	v_mfma_f32_16x16x32_bf16 v[48:51], v[158:161], v[192:195], 0
	v_mfma_f32_16x16x32_bf16 v[36:39], v[150:153], v[200:203], 0
	v_mfma_f32_16x16x32_bf16 v[32:35], v[158:161], v[200:203], 0
	v_mfma_f32_16x16x32_bf16 v[20:23], v[150:153], v[208:211], 0
	v_mfma_f32_16x16x32_bf16 v[16:19], v[158:161], v[208:211], 0
	v_mfma_f32_16x16x32_bf16 v[60:63], v[154:157], v[188:191], v[60:63]
	v_mfma_f32_16x16x32_bf16 v[56:59], v[162:165], v[188:191], v[56:59]
	v_mfma_f32_16x16x32_bf16 v[52:55], v[154:157], v[196:199], v[52:55]
	v_mfma_f32_16x16x32_bf16 v[48:51], v[162:165], v[196:199], v[48:51]
	v_mfma_f32_16x16x32_bf16 v[36:39], v[154:157], v[204:207], v[36:39]
	v_mfma_f32_16x16x32_bf16 v[32:35], v[162:165], v[204:207], v[32:35]
	v_mfma_f32_16x16x32_bf16 v[20:23], v[154:157], v[212:215], v[20:23]
	v_mfma_f32_16x16x32_bf16 v[16:19], v[162:165], v[212:215], v[16:19]
	v_mfma_f32_16x16x32_bf16 v[44:47], v[166:169], v[184:187], 0
	v_mfma_f32_16x16x32_bf16 v[40:43], v[174:177], v[184:187], 0
	v_mfma_f32_16x16x32_bf16 v[28:31], v[166:169], v[192:195], 0
	v_mfma_f32_16x16x32_bf16 v[24:27], v[174:177], v[192:195], 0
	v_mfma_f32_16x16x32_bf16 v[12:15], v[166:169], v[200:203], 0
	v_mfma_f32_16x16x32_bf16 v[8:11], v[174:177], v[200:203], 0
	v_mfma_f32_16x16x32_bf16 v[4:7], v[166:169], v[208:211], 0
	v_mfma_f32_16x16x32_bf16 v[0:3], v[174:177], v[208:211], 0
	v_mfma_f32_16x16x32_bf16 v[44:47], v[170:173], v[188:191], v[44:47]
	v_mfma_f32_16x16x32_bf16 v[40:43], v[178:181], v[188:191], v[40:43]
	v_mfma_f32_16x16x32_bf16 v[28:31], v[170:173], v[196:199], v[28:31]
	v_mfma_f32_16x16x32_bf16 v[24:27], v[178:181], v[196:199], v[24:27]
	v_mfma_f32_16x16x32_bf16 v[12:15], v[170:173], v[204:207], v[12:15]
	v_mfma_f32_16x16x32_bf16 v[8:11], v[178:181], v[204:207], v[8:11]
	v_mfma_f32_16x16x32_bf16 v[4:7], v[170:173], v[212:215], v[4:7]
	v_mfma_f32_16x16x32_bf16 v[0:3], v[178:181], v[212:215], v[0:3]
	s_setprio 0
	s_barrier
	s_add_i32 s60, 0, 0x18000
	s_add_i32 s61, 0, 0x1c000
	v_add_u32_e32 v162, s60, v145
	v_add_u32_e32 v178, s61, v145
	ds_read_b128 v[150:153], v162
	ds_read_b128 v[154:157], v162 offset:1024
	ds_read_b128 v[158:161], v162 offset:2048
	ds_read_b128 v[162:165], v162 offset:3072
	ds_read_b128 v[166:169], v178
	ds_read_b128 v[170:173], v178 offset:1024
	ds_read_b128 v[174:177], v178 offset:2048
	ds_read_b128 v[178:181], v178 offset:3072
	s_add_u32 s30, s30, 0x160000
	s_addc_u32 s31, s31, 0
	s_mov_b32 m0, s41
	v_lshl_add_u64 v[224:225], s[30:31], 0, v[128:129]
	ds_read_b128 v[184:187], v149 offset:32768
	ds_read_b128 v[188:191], v149 offset:33792
	ds_read_b128 v[192:195], v149 offset:34816
	ds_read_b128 v[196:199], v149 offset:35840
	ds_read_b128 v[200:203], v149 offset:36864
	ds_read_b128 v[204:207], v149 offset:37888
	ds_read_b128 v[208:211], v149 offset:38912
	ds_read_b128 v[212:215], v149 offset:39936
	global_load_lds_dwordx4 v[224:225], off
	v_lshl_add_u64 v[224:225], s[30:31], 0, v[132:133]
	s_mov_b32 m0, s42
	s_nop 0
	global_load_lds_dwordx4 v[224:225], off
	s_waitcnt vmcnt(8)
	s_waitcnt lgkmcnt(0)
	s_barrier
	s_setprio 1
	v_mfma_f32_16x16x32_bf16 v[124:127], v[150:153], v[184:187], v[124:127]
	v_mfma_f32_16x16x32_bf16 v[120:123], v[158:161], v[184:187], v[120:123]
	v_mfma_f32_16x16x32_bf16 v[116:119], v[150:153], v[192:195], v[116:119]
	v_mfma_f32_16x16x32_bf16 v[112:115], v[158:161], v[192:195], v[112:115]
	v_mfma_f32_16x16x32_bf16 v[100:103], v[150:153], v[200:203], v[100:103]
	v_mfma_f32_16x16x32_bf16 v[96:99], v[158:161], v[200:203], v[96:99]
	v_mfma_f32_16x16x32_bf16 v[84:87], v[150:153], v[208:211], v[84:87]
	v_mfma_f32_16x16x32_bf16 v[80:83], v[158:161], v[208:211], v[80:83]
	v_mfma_f32_16x16x32_bf16 v[124:127], v[154:157], v[188:191], v[124:127]
	v_mfma_f32_16x16x32_bf16 v[120:123], v[162:165], v[188:191], v[120:123]
	v_mfma_f32_16x16x32_bf16 v[116:119], v[154:157], v[196:199], v[116:119]
	v_mfma_f32_16x16x32_bf16 v[112:115], v[162:165], v[196:199], v[112:115]
	v_mfma_f32_16x16x32_bf16 v[100:103], v[154:157], v[204:207], v[100:103]
	v_mfma_f32_16x16x32_bf16 v[96:99], v[162:165], v[204:207], v[96:99]
	v_mfma_f32_16x16x32_bf16 v[84:87], v[154:157], v[212:215], v[84:87]
	v_mfma_f32_16x16x32_bf16 v[80:83], v[162:165], v[212:215], v[80:83]
	v_mfma_f32_16x16x32_bf16 v[108:111], v[166:169], v[184:187], v[108:111]
	v_mfma_f32_16x16x32_bf16 v[104:107], v[174:177], v[184:187], v[104:107]
	v_mfma_f32_16x16x32_bf16 v[92:95], v[166:169], v[192:195], v[92:95]
	v_mfma_f32_16x16x32_bf16 v[88:91], v[174:177], v[192:195], v[88:91]
	v_mfma_f32_16x16x32_bf16 v[76:79], v[166:169], v[200:203], v[76:79]
	v_mfma_f32_16x16x32_bf16 v[72:75], v[174:177], v[200:203], v[72:75]
	v_mfma_f32_16x16x32_bf16 v[68:71], v[166:169], v[208:211], v[68:71]
	v_mfma_f32_16x16x32_bf16 v[64:67], v[174:177], v[208:211], v[64:67]
	v_mfma_f32_16x16x32_bf16 v[108:111], v[170:173], v[188:191], v[108:111]
	v_mfma_f32_16x16x32_bf16 v[104:107], v[178:181], v[188:191], v[104:107]
	v_mfma_f32_16x16x32_bf16 v[92:95], v[170:173], v[196:199], v[92:95]
	v_mfma_f32_16x16x32_bf16 v[88:91], v[178:181], v[196:199], v[88:91]
	v_mfma_f32_16x16x32_bf16 v[76:79], v[170:173], v[204:207], v[76:79]
	v_mfma_f32_16x16x32_bf16 v[72:75], v[178:181], v[204:207], v[72:75]
	v_mfma_f32_16x16x32_bf16 v[68:71], v[170:173], v[212:215], v[68:71]
	v_mfma_f32_16x16x32_bf16 v[64:67], v[178:181], v[212:215], v[64:67]
	s_setprio 0
	s_barrier
	s_add_i32 s30, s60, s38
	v_lshl_add_u64 v[216:217], v[216:217], 0, s[10:11]
	s_mov_b32 m0, s30
	ds_read_b128 v[184:187], v149 offset:49152
	ds_read_b128 v[188:191], v149 offset:50176
	ds_read_b128 v[192:195], v149 offset:51200
	ds_read_b128 v[196:199], v149 offset:52224
	ds_read_b128 v[200:203], v149 offset:53248
	ds_read_b128 v[204:207], v149 offset:54272
	ds_read_b128 v[208:211], v149 offset:55296
	ds_read_b128 v[212:215], v149 offset:56320
	global_load_lds_dwordx4 v[216:217], off
	s_add_i32 m0, s30, 0x2000
	s_add_u32 s28, s28, 0x80080
	v_lshl_add_u64 v[216:217], v[218:219], 0, s[10:11]
	s_addc_u32 s29, s29, 0
	s_add_i32 s30, s61, s38
	global_load_lds_dwordx4 v[216:217], off
	v_lshl_add_u64 v[216:217], s[28:29], 0, v[130:131]
	s_mov_b32 m0, s30
	s_nop 0
	global_load_lds_dwordx4 v[216:217], off
	v_lshl_add_u64 v[216:217], s[28:29], 0, v[134:135]
	s_add_i32 m0, s30, 0x2000
	s_nop 0
	global_load_lds_dwordx4 v[216:217], off
	v_lshl_add_u64 v[216:217], v[220:221], 0, s[10:11]
	s_mov_b32 m0, s45
	s_nop 0
	global_load_lds_dwordx4 v[216:217], off
	v_lshl_add_u64 v[216:217], v[222:223], 0, s[10:11]
	s_mov_b32 m0, s46
	s_nop 0
	global_load_lds_dwordx4 v[216:217], off
	s_waitcnt vmcnt(8)
	s_waitcnt lgkmcnt(0)
	s_barrier
	s_setprio 1
	v_mfma_f32_16x16x32_bf16 v[60:63], v[150:153], v[184:187], v[60:63]
	v_mfma_f32_16x16x32_bf16 v[56:59], v[158:161], v[184:187], v[56:59]
	v_mfma_f32_16x16x32_bf16 v[52:55], v[150:153], v[192:195], v[52:55]
	v_mfma_f32_16x16x32_bf16 v[48:51], v[158:161], v[192:195], v[48:51]
	v_mfma_f32_16x16x32_bf16 v[36:39], v[150:153], v[200:203], v[36:39]
	v_mfma_f32_16x16x32_bf16 v[32:35], v[158:161], v[200:203], v[32:35]
	v_mfma_f32_16x16x32_bf16 v[20:23], v[150:153], v[208:211], v[20:23]
	v_mfma_f32_16x16x32_bf16 v[16:19], v[158:161], v[208:211], v[16:19]
	v_mfma_f32_16x16x32_bf16 v[60:63], v[154:157], v[188:191], v[60:63]
	v_mfma_f32_16x16x32_bf16 v[56:59], v[162:165], v[188:191], v[56:59]
	v_mfma_f32_16x16x32_bf16 v[52:55], v[154:157], v[196:199], v[52:55]
	v_mfma_f32_16x16x32_bf16 v[48:51], v[162:165], v[196:199], v[48:51]
	v_mfma_f32_16x16x32_bf16 v[36:39], v[154:157], v[204:207], v[36:39]
	v_mfma_f32_16x16x32_bf16 v[32:35], v[162:165], v[204:207], v[32:35]
	v_mfma_f32_16x16x32_bf16 v[20:23], v[154:157], v[212:215], v[20:23]
	v_mfma_f32_16x16x32_bf16 v[16:19], v[162:165], v[212:215], v[16:19]
	v_mfma_f32_16x16x32_bf16 v[44:47], v[166:169], v[184:187], v[44:47]
	v_mfma_f32_16x16x32_bf16 v[40:43], v[174:177], v[184:187], v[40:43]
	v_mfma_f32_16x16x32_bf16 v[28:31], v[166:169], v[192:195], v[28:31]
	v_mfma_f32_16x16x32_bf16 v[24:27], v[174:177], v[192:195], v[24:27]
	v_mfma_f32_16x16x32_bf16 v[12:15], v[166:169], v[200:203], v[12:15]
	v_mfma_f32_16x16x32_bf16 v[8:11], v[174:177], v[200:203], v[8:11]
	v_mfma_f32_16x16x32_bf16 v[4:7], v[166:169], v[208:211], v[4:7]
	v_mfma_f32_16x16x32_bf16 v[0:3], v[174:177], v[208:211], v[0:3]
	v_mfma_f32_16x16x32_bf16 v[44:47], v[170:173], v[188:191], v[44:47]
	v_mfma_f32_16x16x32_bf16 v[40:43], v[178:181], v[188:191], v[40:43]
	v_mfma_f32_16x16x32_bf16 v[28:31], v[170:173], v[196:199], v[28:31]
	v_mfma_f32_16x16x32_bf16 v[24:27], v[178:181], v[196:199], v[24:27]
	v_mfma_f32_16x16x32_bf16 v[12:15], v[170:173], v[204:207], v[12:15]
	v_mfma_f32_16x16x32_bf16 v[8:11], v[178:181], v[204:207], v[8:11]
	v_mfma_f32_16x16x32_bf16 v[4:7], v[170:173], v[212:215], v[4:7]
	v_mfma_f32_16x16x32_bf16 v[0:3], v[178:181], v[212:215], v[0:3]
	s_setprio 0
	s_barrier
	s_add_i32 s59, s59, 2
	s_add_u32 s4, s4, 0x100
	s_addc_u32 s5, s5, 0
	s_add_u32 s57, s57, 0x100
	s_addc_u32 s58, s58, 0
	.p2align	6

.LBB0_1408:
	s_ashr_i32 s15, s14, 31
	s_lshl_b64 s[16:17], s[14:15], 19
	s_add_u32 s16, s28, s16
	s_addc_u32 s17, s29, s17
	s_and_b64 s[18:19], s[0:1], exec
	s_cselect_b32 s15, s17, s23
	s_cselect_b32 s47, s16, s22
	s_ashr_i32 s13, s12, 31
	s_lshl_b64 s[18:19], s[12:13], 19
	s_add_u32 s18, s30, s18
	s_addc_u32 s19, s31, s19
	s_and_b64 s[26:27], s[0:1], exec
	s_cselect_b32 s13, s19, s25
	s_cselect_b32 s48, s18, s24
	s_add_u32 s22, s22, 0x40080
	s_addc_u32 s23, s23, 0
	s_add_u32 s49, s24, 0x100
	s_addc_u32 s50, s25, 0
	s_mov_b32 s51, -2
	s_waitcnt lgkmcnt(0)
	ds_read_b128 v[152:155], v149
	ds_read_b128 v[156:159], v149 offset:1024
	ds_read_b128 v[160:163], v149 offset:2048
	ds_read_b128 v[164:167], v149 offset:3072
	ds_read_b128 v[168:171], v150
	ds_read_b128 v[172:175], v150 offset:1024
	ds_read_b128 v[176:179], v150 offset:2048
	ds_read_b128 v[184:187], v150 offset:3072
	s_add_u32 s24, s22, 0xfffc0080
	s_addc_u32 s25, s23, -1
	s_cmp_eq_u32 s51, 12
	s_cselect_b32 s27, s15, s25
	s_cselect_b32 s26, s47, s24
	s_cselect_b32 s25, s13, s50
	s_cselect_b32 s24, s48, s49
	v_lshl_add_u64 v[144:145], s[22:23], 0, v[136:137]
	s_add_i32 m0, s21, 0xc000
	ds_read_b128 v[188:191], v151
	ds_read_b128 v[192:195], v151 offset:1024
	ds_read_b128 v[196:199], v151 offset:2048
	ds_read_b128 v[200:203], v151 offset:3072
	ds_read_b128 v[204:207], v151 offset:4096
	ds_read_b128 v[208:211], v151 offset:5120
	ds_read_b128 v[212:215], v151 offset:6144
	ds_read_b128 v[216:219], v151 offset:7168
	global_load_lds_dwordx4 v[144:145], off
	v_lshl_add_u64 v[144:145], s[22:23], 0, v[138:139]
	s_add_i32 m0, s21, 0xe000
	s_nop 0
	global_load_lds_dwordx4 v[144:145], off
	s_waitcnt vmcnt(8)
	s_waitcnt lgkmcnt(0)
	s_barrier
	s_setprio 1
	v_mfma_f32_16x16x32_bf16 v[124:127], v[152:155], v[188:191], 0
	v_mfma_f32_16x16x32_bf16 v[120:123], v[160:163], v[188:191], 0
	v_mfma_f32_16x16x32_bf16 v[108:111], v[152:155], v[196:199], 0
	v_mfma_f32_16x16x32_bf16 v[104:107], v[160:163], v[196:199], 0
	v_mfma_f32_16x16x32_bf16 v[92:95], v[152:155], v[204:207], 0
	v_mfma_f32_16x16x32_bf16 v[88:91], v[160:163], v[204:207], 0
	v_mfma_f32_16x16x32_bf16 v[76:79], v[152:155], v[212:215], 0
	v_mfma_f32_16x16x32_bf16 v[72:75], v[160:163], v[212:215], 0
	v_mfma_f32_16x16x32_bf16 v[124:127], v[156:159], v[192:195], v[124:127]
	v_mfma_f32_16x16x32_bf16 v[120:123], v[164:167], v[192:195], v[120:123]
	v_mfma_f32_16x16x32_bf16 v[108:111], v[156:159], v[200:203], v[108:111]
	v_mfma_f32_16x16x32_bf16 v[104:107], v[164:167], v[200:203], v[104:107]
	v_mfma_f32_16x16x32_bf16 v[92:95], v[156:159], v[208:211], v[92:95]
	v_mfma_f32_16x16x32_bf16 v[88:91], v[164:167], v[208:211], v[88:91]
	v_mfma_f32_16x16x32_bf16 v[76:79], v[156:159], v[216:219], v[76:79]
	v_mfma_f32_16x16x32_bf16 v[72:75], v[164:167], v[216:219], v[72:75]
	v_mfma_f32_16x16x32_bf16 v[116:119], v[168:171], v[188:191], 0
	v_mfma_f32_16x16x32_bf16 v[112:115], v[176:179], v[188:191], 0
	v_mfma_f32_16x16x32_bf16 v[100:103], v[168:171], v[196:199], 0
	v_mfma_f32_16x16x32_bf16 v[96:99], v[176:179], v[196:199], 0
	v_mfma_f32_16x16x32_bf16 v[84:87], v[168:171], v[204:207], 0
	v_mfma_f32_16x16x32_bf16 v[80:83], v[176:179], v[204:207], 0
	v_mfma_f32_16x16x32_bf16 v[68:71], v[168:171], v[212:215], 0
	v_mfma_f32_16x16x32_bf16 v[64:67], v[176:179], v[212:215], 0
	v_mfma_f32_16x16x32_bf16 v[116:119], v[172:175], v[192:195], v[116:119]
	v_mfma_f32_16x16x32_bf16 v[112:115], v[184:187], v[192:195], v[112:115]
	v_mfma_f32_16x16x32_bf16 v[100:103], v[172:175], v[200:203], v[100:103]
	v_mfma_f32_16x16x32_bf16 v[96:99], v[184:187], v[200:203], v[96:99]
	v_mfma_f32_16x16x32_bf16 v[84:87], v[172:175], v[208:211], v[84:87]
	v_mfma_f32_16x16x32_bf16 v[80:83], v[184:187], v[208:211], v[80:83]
	v_mfma_f32_16x16x32_bf16 v[68:71], v[172:175], v[216:219], v[68:71]
	v_mfma_f32_16x16x32_bf16 v[64:67], v[184:187], v[216:219], v[64:67]
	s_setprio 0
	s_barrier
	s_add_i32 s52, s43, s34
	v_lshl_add_u64 v[144:145], s[24:25], 0, v[130:131]
	s_mov_b32 m0, s52
	ds_read_b128 v[188:191], v151 offset:16384
	ds_read_b128 v[192:195], v151 offset:17408
	ds_read_b128 v[196:199], v151 offset:18432
	ds_read_b128 v[200:203], v151 offset:19456
	ds_read_b128 v[204:207], v151 offset:20480
	ds_read_b128 v[208:211], v151 offset:21504
	ds_read_b128 v[212:215], v151 offset:22528
	ds_read_b128 v[216:219], v151 offset:23552
	global_load_lds_dwordx4 v[144:145], off
	s_add_i32 m0, s52, 0x2000
	s_add_u32 s52, s24, 0x40000
	v_lshl_add_u64 v[180:181], s[24:25], 0, v[134:135]
	s_addc_u32 s53, s25, 0
	s_add_i32 s54, s44, s34
	global_load_lds_dwordx4 v[180:181], off
	v_lshl_add_u64 v[220:221], s[52:53], 0, v[130:131]
	s_mov_b32 m0, s54
	v_lshl_add_u64 v[222:223], s[26:27], 0, v[132:133]
	global_load_lds_dwordx4 v[220:221], off
	v_lshl_add_u64 v[220:221], s[52:53], 0, v[134:135]
	s_add_i32 m0, s54, 0x2000
	s_nop 0
	global_load_lds_dwordx4 v[220:221], off
	v_lshl_add_u64 v[220:221], s[26:27], 0, v[128:129]
	s_mov_b32 m0, s21
	s_nop 0
	global_load_lds_dwordx4 v[220:221], off
	s_mov_b32 m0, s36
	s_nop 0
	global_load_lds_dwordx4 v[222:223], off
	s_waitcnt vmcnt(8)
	s_waitcnt lgkmcnt(0)
	s_barrier
	s_setprio 1
	v_mfma_f32_16x16x32_bf16 v[60:63], v[152:155], v[188:191], 0
	v_mfma_f32_16x16x32_bf16 v[56:59], v[160:163], v[188:191], 0
	v_mfma_f32_16x16x32_bf16 v[44:47], v[152:155], v[196:199], 0
	v_mfma_f32_16x16x32_bf16 v[40:43], v[160:163], v[196:199], 0
	v_mfma_f32_16x16x32_bf16 v[28:31], v[152:155], v[204:207], 0
	v_mfma_f32_16x16x32_bf16 v[24:27], v[160:163], v[204:207], 0
	v_mfma_f32_16x16x32_bf16 v[12:15], v[152:155], v[212:215], 0
	v_mfma_f32_16x16x32_bf16 v[8:11], v[160:163], v[212:215], 0
	v_mfma_f32_16x16x32_bf16 v[60:63], v[156:159], v[192:195], v[60:63]
	v_mfma_f32_16x16x32_bf16 v[56:59], v[164:167], v[192:195], v[56:59]
	v_mfma_f32_16x16x32_bf16 v[44:47], v[156:159], v[200:203], v[44:47]
	v_mfma_f32_16x16x32_bf16 v[40:43], v[164:167], v[200:203], v[40:43]
	v_mfma_f32_16x16x32_bf16 v[28:31], v[156:159], v[208:211], v[28:31]
	v_mfma_f32_16x16x32_bf16 v[24:27], v[164:167], v[208:211], v[24:27]
	v_mfma_f32_16x16x32_bf16 v[12:15], v[156:159], v[216:219], v[12:15]
	v_mfma_f32_16x16x32_bf16 v[8:11], v[164:167], v[216:219], v[8:11]
	v_mfma_f32_16x16x32_bf16 v[52:55], v[168:171], v[188:191], 0
	v_mfma_f32_16x16x32_bf16 v[48:51], v[176:179], v[188:191], 0
	v_mfma_f32_16x16x32_bf16 v[36:39], v[168:171], v[196:199], 0
	v_mfma_f32_16x16x32_bf16 v[32:35], v[176:179], v[196:199], 0
	v_mfma_f32_16x16x32_bf16 v[20:23], v[168:171], v[204:207], 0
	v_mfma_f32_16x16x32_bf16 v[16:19], v[176:179], v[204:207], 0
	v_mfma_f32_16x16x32_bf16 v[4:7], v[168:171], v[212:215], 0
	v_mfma_f32_16x16x32_bf16 v[0:3], v[176:179], v[212:215], 0
	v_mfma_f32_16x16x32_bf16 v[52:55], v[172:175], v[192:195], v[52:55]
	v_mfma_f32_16x16x32_bf16 v[48:51], v[184:187], v[192:195], v[48:51]
	v_mfma_f32_16x16x32_bf16 v[36:39], v[172:175], v[200:203], v[36:39]
	v_mfma_f32_16x16x32_bf16 v[32:35], v[184:187], v[200:203], v[32:35]
	v_mfma_f32_16x16x32_bf16 v[20:23], v[172:175], v[208:211], v[20:23]
	v_mfma_f32_16x16x32_bf16 v[16:19], v[184:187], v[208:211], v[16:19]
	v_mfma_f32_16x16x32_bf16 v[4:7], v[172:175], v[216:219], v[4:7]
	v_mfma_f32_16x16x32_bf16 v[0:3], v[184:187], v[216:219], v[0:3]
	s_setprio 0
	s_barrier
	s_add_i32 s52, 0, 0x18000
	s_add_i32 s53, 0, 0x1c000
	v_add_u32_e32 v164, s52, v147
	v_add_u32_e32 v183, s53, v147
	ds_read_b128 v[152:155], v164
	ds_read_b128 v[156:159], v164 offset:1024
	ds_read_b128 v[160:163], v164 offset:2048
	ds_read_b128 v[164:167], v164 offset:3072
	ds_read_b128 v[168:171], v183
	ds_read_b128 v[172:175], v183 offset:1024
	ds_read_b128 v[176:179], v183 offset:2048
	ds_read_b128 v[184:187], v183 offset:3072
	s_add_u32 s26, s26, 0x40000
	s_addc_u32 s27, s27, 0
	s_mov_b32 m0, s37
	v_lshl_add_u64 v[224:225], s[26:27], 0, v[128:129]
	ds_read_b128 v[188:191], v151 offset:32768
	ds_read_b128 v[192:195], v151 offset:33792
	ds_read_b128 v[196:199], v151 offset:34816
	ds_read_b128 v[200:203], v151 offset:35840
	ds_read_b128 v[204:207], v151 offset:36864
	ds_read_b128 v[208:211], v151 offset:37888
	ds_read_b128 v[212:215], v151 offset:38912
	ds_read_b128 v[216:219], v151 offset:39936
	global_load_lds_dwordx4 v[224:225], off
	v_lshl_add_u64 v[224:225], s[26:27], 0, v[132:133]
	s_mov_b32 m0, s38
	s_nop 0
	global_load_lds_dwordx4 v[224:225], off
	s_waitcnt vmcnt(8)
	s_waitcnt lgkmcnt(0)
	s_barrier
	s_setprio 1
	v_mfma_f32_16x16x32_bf16 v[124:127], v[152:155], v[188:191], v[124:127]
	v_mfma_f32_16x16x32_bf16 v[120:123], v[160:163], v[188:191], v[120:123]
	v_mfma_f32_16x16x32_bf16 v[108:111], v[152:155], v[196:199], v[108:111]
	v_mfma_f32_16x16x32_bf16 v[104:107], v[160:163], v[196:199], v[104:107]
	v_mfma_f32_16x16x32_bf16 v[92:95], v[152:155], v[204:207], v[92:95]
	v_mfma_f32_16x16x32_bf16 v[88:91], v[160:163], v[204:207], v[88:91]
	v_mfma_f32_16x16x32_bf16 v[76:79], v[152:155], v[212:215], v[76:79]
	v_mfma_f32_16x16x32_bf16 v[72:75], v[160:163], v[212:215], v[72:75]
	v_mfma_f32_16x16x32_bf16 v[124:127], v[156:159], v[192:195], v[124:127]
	v_mfma_f32_16x16x32_bf16 v[120:123], v[164:167], v[192:195], v[120:123]
	v_mfma_f32_16x16x32_bf16 v[108:111], v[156:159], v[200:203], v[108:111]
	v_mfma_f32_16x16x32_bf16 v[104:107], v[164:167], v[200:203], v[104:107]
	v_mfma_f32_16x16x32_bf16 v[92:95], v[156:159], v[208:211], v[92:95]
	v_mfma_f32_16x16x32_bf16 v[88:91], v[164:167], v[208:211], v[88:91]
	v_mfma_f32_16x16x32_bf16 v[76:79], v[156:159], v[216:219], v[76:79]
	v_mfma_f32_16x16x32_bf16 v[72:75], v[164:167], v[216:219], v[72:75]
	v_mfma_f32_16x16x32_bf16 v[116:119], v[168:171], v[188:191], v[116:119]
	v_mfma_f32_16x16x32_bf16 v[112:115], v[176:179], v[188:191], v[112:115]
	v_mfma_f32_16x16x32_bf16 v[100:103], v[168:171], v[196:199], v[100:103]
	v_mfma_f32_16x16x32_bf16 v[96:99], v[176:179], v[196:199], v[96:99]
	v_mfma_f32_16x16x32_bf16 v[84:87], v[168:171], v[204:207], v[84:87]
	v_mfma_f32_16x16x32_bf16 v[80:83], v[176:179], v[204:207], v[80:83]
	v_mfma_f32_16x16x32_bf16 v[68:71], v[168:171], v[212:215], v[68:71]
	v_mfma_f32_16x16x32_bf16 v[64:67], v[176:179], v[212:215], v[64:67]
	v_mfma_f32_16x16x32_bf16 v[116:119], v[172:175], v[192:195], v[116:119]
	v_mfma_f32_16x16x32_bf16 v[112:115], v[184:187], v[192:195], v[112:115]
	v_mfma_f32_16x16x32_bf16 v[100:103], v[172:175], v[200:203], v[100:103]
	v_mfma_f32_16x16x32_bf16 v[96:99], v[184:187], v[200:203], v[96:99]
	v_mfma_f32_16x16x32_bf16 v[84:87], v[172:175], v[208:211], v[84:87]
	v_mfma_f32_16x16x32_bf16 v[80:83], v[184:187], v[208:211], v[80:83]
	v_mfma_f32_16x16x32_bf16 v[68:71], v[172:175], v[216:219], v[68:71]
	v_mfma_f32_16x16x32_bf16 v[64:67], v[184:187], v[216:219], v[64:67]
	s_setprio 0
	s_barrier
	s_add_i32 s26, s52, s34
	v_lshl_add_u64 v[144:145], v[144:145], 0, s[8:9]
	s_mov_b32 m0, s26
	ds_read_b128 v[188:191], v151 offset:49152
	ds_read_b128 v[192:195], v151 offset:50176
	ds_read_b128 v[196:199], v151 offset:51200
	ds_read_b128 v[200:203], v151 offset:52224
	ds_read_b128 v[204:207], v151 offset:53248
	ds_read_b128 v[208:211], v151 offset:54272
	ds_read_b128 v[212:215], v151 offset:55296
	ds_read_b128 v[216:219], v151 offset:56320
	global_load_lds_dwordx4 v[144:145], off
	s_add_i32 m0, s26, 0x2000
	s_add_u32 s24, s24, 0x40080
	v_lshl_add_u64 v[144:145], v[180:181], 0, s[8:9]
	s_addc_u32 s25, s25, 0
	s_add_i32 s26, s53, s34
	global_load_lds_dwordx4 v[144:145], off
	v_lshl_add_u64 v[144:145], s[24:25], 0, v[130:131]
	s_mov_b32 m0, s26
	s_nop 0
	global_load_lds_dwordx4 v[144:145], off
	v_lshl_add_u64 v[144:145], s[24:25], 0, v[134:135]
	s_add_i32 m0, s26, 0x2000
	s_nop 0
	global_load_lds_dwordx4 v[144:145], off
	v_lshl_add_u64 v[144:145], v[220:221], 0, s[8:9]
	s_mov_b32 m0, s41
	s_nop 0
	global_load_lds_dwordx4 v[144:145], off
	v_lshl_add_u64 v[144:145], v[222:223], 0, s[8:9]
	s_mov_b32 m0, s42
	s_nop 0
	global_load_lds_dwordx4 v[144:145], off
	s_waitcnt vmcnt(8)
	s_waitcnt lgkmcnt(0)
	s_barrier
	s_setprio 1
	v_mfma_f32_16x16x32_bf16 v[60:63], v[152:155], v[188:191], v[60:63]
	v_mfma_f32_16x16x32_bf16 v[56:59], v[160:163], v[188:191], v[56:59]
	v_mfma_f32_16x16x32_bf16 v[44:47], v[152:155], v[196:199], v[44:47]
	v_mfma_f32_16x16x32_bf16 v[40:43], v[160:163], v[196:199], v[40:43]
	v_mfma_f32_16x16x32_bf16 v[28:31], v[152:155], v[204:207], v[28:31]
	v_mfma_f32_16x16x32_bf16 v[24:27], v[160:163], v[204:207], v[24:27]
	v_mfma_f32_16x16x32_bf16 v[12:15], v[152:155], v[212:215], v[12:15]
	v_mfma_f32_16x16x32_bf16 v[8:11], v[160:163], v[212:215], v[8:11]
	v_mfma_f32_16x16x32_bf16 v[60:63], v[156:159], v[192:195], v[60:63]
	v_mfma_f32_16x16x32_bf16 v[56:59], v[164:167], v[192:195], v[56:59]
	v_mfma_f32_16x16x32_bf16 v[44:47], v[156:159], v[200:203], v[44:47]
	v_mfma_f32_16x16x32_bf16 v[40:43], v[164:167], v[200:203], v[40:43]
	v_mfma_f32_16x16x32_bf16 v[28:31], v[156:159], v[208:211], v[28:31]
	v_mfma_f32_16x16x32_bf16 v[24:27], v[164:167], v[208:211], v[24:27]
	v_mfma_f32_16x16x32_bf16 v[12:15], v[156:159], v[216:219], v[12:15]
	v_mfma_f32_16x16x32_bf16 v[8:11], v[164:167], v[216:219], v[8:11]
	v_mfma_f32_16x16x32_bf16 v[52:55], v[168:171], v[188:191], v[52:55]
	v_mfma_f32_16x16x32_bf16 v[48:51], v[176:179], v[188:191], v[48:51]
	v_mfma_f32_16x16x32_bf16 v[36:39], v[168:171], v[196:199], v[36:39]
	v_mfma_f32_16x16x32_bf16 v[32:35], v[176:179], v[196:199], v[32:35]
	v_mfma_f32_16x16x32_bf16 v[20:23], v[168:171], v[204:207], v[20:23]
	v_mfma_f32_16x16x32_bf16 v[16:19], v[176:179], v[204:207], v[16:19]
	v_mfma_f32_16x16x32_bf16 v[4:7], v[168:171], v[212:215], v[4:7]
	v_mfma_f32_16x16x32_bf16 v[0:3], v[176:179], v[212:215], v[0:3]
	v_mfma_f32_16x16x32_bf16 v[52:55], v[172:175], v[192:195], v[52:55]
	v_mfma_f32_16x16x32_bf16 v[48:51], v[184:187], v[192:195], v[48:51]
	v_mfma_f32_16x16x32_bf16 v[36:39], v[172:175], v[200:203], v[36:39]
	v_mfma_f32_16x16x32_bf16 v[32:35], v[184:187], v[200:203], v[32:35]
	v_mfma_f32_16x16x32_bf16 v[20:23], v[172:175], v[208:211], v[20:23]
	v_mfma_f32_16x16x32_bf16 v[16:19], v[184:187], v[208:211], v[16:19]
	v_mfma_f32_16x16x32_bf16 v[4:7], v[172:175], v[216:219], v[4:7]
	v_mfma_f32_16x16x32_bf16 v[0:3], v[184:187], v[216:219], v[0:3]
	s_setprio 0
	s_barrier
	s_add_i32 s51, s51, 2
	s_add_u32 s22, s22, 0x100
	s_addc_u32 s23, s23, 0
	s_add_u32 s49, s49, 0x100
	s_addc_u32 s50, s50, 0
	.p2align	6

.LBB0_1487:
	s_add_u32 s24, s24, 0xb0080
	s_addc_u32 s25, s25, 0
	s_add_u32 s55, s26, 0x100
	s_addc_u32 s56, s27, 0
	s_mov_b32 s57, -2
	s_waitcnt lgkmcnt(0)
	ds_read_b128 v[150:153], v147
	ds_read_b128 v[154:157], v147 offset:1024
	ds_read_b128 v[158:161], v147 offset:2048
	ds_read_b128 v[162:165], v147 offset:3072
	ds_read_b128 v[166:169], v148
	ds_read_b128 v[170:173], v148 offset:1024
	ds_read_b128 v[174:177], v148 offset:2048
	ds_read_b128 v[178:181], v148 offset:3072
	s_add_u32 s26, s24, 0xfff50080
	s_addc_u32 s27, s25, -1
	s_cmp_eq_u32 s57, 40
	s_cselect_b32 s29, s5, s27
	s_cselect_b32 s28, s4, s26
	s_cselect_b32 s27, s23, s56
	s_cselect_b32 s26, s22, s55
	v_lshl_add_u64 v[216:217], s[24:25], 0, v[136:137]
	s_add_i32 m0, s37, 0xc000
	ds_read_b128 v[184:187], v149
	ds_read_b128 v[188:191], v149 offset:1024
	ds_read_b128 v[192:195], v149 offset:2048
	ds_read_b128 v[196:199], v149 offset:3072
	ds_read_b128 v[200:203], v149 offset:4096
	ds_read_b128 v[204:207], v149 offset:5120
	ds_read_b128 v[208:211], v149 offset:6144
	ds_read_b128 v[212:215], v149 offset:7168
	global_load_lds_dwordx4 v[216:217], off
	v_lshl_add_u64 v[216:217], s[24:25], 0, v[138:139]
	s_add_i32 m0, s37, 0xe000
	s_nop 0
	global_load_lds_dwordx4 v[216:217], off
	s_waitcnt vmcnt(8)
	s_waitcnt lgkmcnt(0)
	s_barrier
	s_setprio 1
	v_mfma_f32_16x16x32_bf16 v[124:127], v[150:153], v[184:187], 0
	v_mfma_f32_16x16x32_bf16 v[120:123], v[158:161], v[184:187], 0
	v_mfma_f32_16x16x32_bf16 v[116:119], v[150:153], v[192:195], 0
	v_mfma_f32_16x16x32_bf16 v[112:115], v[158:161], v[192:195], 0
	v_mfma_f32_16x16x32_bf16 v[100:103], v[150:153], v[200:203], 0
	v_mfma_f32_16x16x32_bf16 v[96:99], v[158:161], v[200:203], 0
	v_mfma_f32_16x16x32_bf16 v[84:87], v[150:153], v[208:211], 0
	v_mfma_f32_16x16x32_bf16 v[80:83], v[158:161], v[208:211], 0
	v_mfma_f32_16x16x32_bf16 v[124:127], v[154:157], v[188:191], v[124:127]
	v_mfma_f32_16x16x32_bf16 v[120:123], v[162:165], v[188:191], v[120:123]
	v_mfma_f32_16x16x32_bf16 v[116:119], v[154:157], v[196:199], v[116:119]
	v_mfma_f32_16x16x32_bf16 v[112:115], v[162:165], v[196:199], v[112:115]
	v_mfma_f32_16x16x32_bf16 v[100:103], v[154:157], v[204:207], v[100:103]
	v_mfma_f32_16x16x32_bf16 v[96:99], v[162:165], v[204:207], v[96:99]
	v_mfma_f32_16x16x32_bf16 v[84:87], v[154:157], v[212:215], v[84:87]
	v_mfma_f32_16x16x32_bf16 v[80:83], v[162:165], v[212:215], v[80:83]
	v_mfma_f32_16x16x32_bf16 v[108:111], v[166:169], v[184:187], 0
	v_mfma_f32_16x16x32_bf16 v[104:107], v[174:177], v[184:187], 0
	v_mfma_f32_16x16x32_bf16 v[92:95], v[166:169], v[192:195], 0
	v_mfma_f32_16x16x32_bf16 v[88:91], v[174:177], v[192:195], 0
	v_mfma_f32_16x16x32_bf16 v[76:79], v[166:169], v[200:203], 0
	v_mfma_f32_16x16x32_bf16 v[72:75], v[174:177], v[200:203], 0
	v_mfma_f32_16x16x32_bf16 v[68:71], v[166:169], v[208:211], 0
	v_mfma_f32_16x16x32_bf16 v[64:67], v[174:177], v[208:211], 0
	v_mfma_f32_16x16x32_bf16 v[108:111], v[170:173], v[188:191], v[108:111]
	v_mfma_f32_16x16x32_bf16 v[104:107], v[178:181], v[188:191], v[104:107]
	v_mfma_f32_16x16x32_bf16 v[92:95], v[170:173], v[196:199], v[92:95]
	v_mfma_f32_16x16x32_bf16 v[88:91], v[178:181], v[196:199], v[88:91]
	v_mfma_f32_16x16x32_bf16 v[76:79], v[170:173], v[204:207], v[76:79]
	v_mfma_f32_16x16x32_bf16 v[72:75], v[178:181], v[204:207], v[72:75]
	v_mfma_f32_16x16x32_bf16 v[68:71], v[170:173], v[212:215], v[68:71]
	v_mfma_f32_16x16x32_bf16 v[64:67], v[178:181], v[212:215], v[64:67]
	s_setprio 0
	s_barrier
	s_add_i32 s58, s45, s36
	v_lshl_add_u64 v[216:217], s[26:27], 0, v[130:131]
	s_mov_b32 m0, s58
	ds_read_b128 v[184:187], v149 offset:16384
	ds_read_b128 v[188:191], v149 offset:17408
	ds_read_b128 v[192:195], v149 offset:18432
	ds_read_b128 v[196:199], v149 offset:19456
	ds_read_b128 v[200:203], v149 offset:20480
	ds_read_b128 v[204:207], v149 offset:21504
	ds_read_b128 v[208:211], v149 offset:22528
	ds_read_b128 v[212:215], v149 offset:23552
	global_load_lds_dwordx4 v[216:217], off
	s_add_i32 m0, s58, 0x2000
	s_add_u32 s58, s26, 0xb0000
	v_lshl_add_u64 v[218:219], s[26:27], 0, v[134:135]
	s_addc_u32 s59, s27, 0
	s_add_i32 s60, s46, s36
	global_load_lds_dwordx4 v[218:219], off
	v_lshl_add_u64 v[220:221], s[58:59], 0, v[130:131]
	s_mov_b32 m0, s60
	v_lshl_add_u64 v[222:223], s[28:29], 0, v[132:133]
	global_load_lds_dwordx4 v[220:221], off
	v_lshl_add_u64 v[220:221], s[58:59], 0, v[134:135]
	s_add_i32 m0, s60, 0x2000
	s_nop 0
	global_load_lds_dwordx4 v[220:221], off
	v_lshl_add_u64 v[220:221], s[28:29], 0, v[128:129]
	s_mov_b32 m0, s37
	s_nop 0
	global_load_lds_dwordx4 v[220:221], off
	s_mov_b32 m0, s38
	s_nop 0
	global_load_lds_dwordx4 v[222:223], off
	s_waitcnt vmcnt(8)
	s_waitcnt lgkmcnt(0)
	s_barrier
	s_setprio 1
	v_mfma_f32_16x16x32_bf16 v[60:63], v[150:153], v[184:187], 0
	v_mfma_f32_16x16x32_bf16 v[56:59], v[158:161], v[184:187], 0
	v_mfma_f32_16x16x32_bf16 v[52:55], v[150:153], v[192:195], 0
	v_mfma_f32_16x16x32_bf16 v[48:51], v[158:161], v[192:195], 0
	v_mfma_f32_16x16x32_bf16 v[36:39], v[150:153], v[200:203], 0
	v_mfma_f32_16x16x32_bf16 v[32:35], v[158:161], v[200:203], 0
	v_mfma_f32_16x16x32_bf16 v[20:23], v[150:153], v[208:211], 0
	v_mfma_f32_16x16x32_bf16 v[16:19], v[158:161], v[208:211], 0
	v_mfma_f32_16x16x32_bf16 v[60:63], v[154:157], v[188:191], v[60:63]
	v_mfma_f32_16x16x32_bf16 v[56:59], v[162:165], v[188:191], v[56:59]
	v_mfma_f32_16x16x32_bf16 v[52:55], v[154:157], v[196:199], v[52:55]
	v_mfma_f32_16x16x32_bf16 v[48:51], v[162:165], v[196:199], v[48:51]
	v_mfma_f32_16x16x32_bf16 v[36:39], v[154:157], v[204:207], v[36:39]
	v_mfma_f32_16x16x32_bf16 v[32:35], v[162:165], v[204:207], v[32:35]
	v_mfma_f32_16x16x32_bf16 v[20:23], v[154:157], v[212:215], v[20:23]
	v_mfma_f32_16x16x32_bf16 v[16:19], v[162:165], v[212:215], v[16:19]
	v_mfma_f32_16x16x32_bf16 v[44:47], v[166:169], v[184:187], 0
	v_mfma_f32_16x16x32_bf16 v[40:43], v[174:177], v[184:187], 0
	v_mfma_f32_16x16x32_bf16 v[28:31], v[166:169], v[192:195], 0
	v_mfma_f32_16x16x32_bf16 v[24:27], v[174:177], v[192:195], 0
	v_mfma_f32_16x16x32_bf16 v[12:15], v[166:169], v[200:203], 0
	v_mfma_f32_16x16x32_bf16 v[8:11], v[174:177], v[200:203], 0
	v_mfma_f32_16x16x32_bf16 v[4:7], v[166:169], v[208:211], 0
	v_mfma_f32_16x16x32_bf16 v[0:3], v[174:177], v[208:211], 0
	v_mfma_f32_16x16x32_bf16 v[44:47], v[170:173], v[188:191], v[44:47]
	v_mfma_f32_16x16x32_bf16 v[40:43], v[178:181], v[188:191], v[40:43]
	v_mfma_f32_16x16x32_bf16 v[28:31], v[170:173], v[196:199], v[28:31]
	v_mfma_f32_16x16x32_bf16 v[24:27], v[178:181], v[196:199], v[24:27]
	v_mfma_f32_16x16x32_bf16 v[12:15], v[170:173], v[204:207], v[12:15]
	v_mfma_f32_16x16x32_bf16 v[8:11], v[178:181], v[204:207], v[8:11]
	v_mfma_f32_16x16x32_bf16 v[4:7], v[170:173], v[212:215], v[4:7]
	v_mfma_f32_16x16x32_bf16 v[0:3], v[178:181], v[212:215], v[0:3]
	s_setprio 0
	s_barrier
	s_add_i32 s58, 0, 0x18000
	s_add_i32 s59, 0, 0x1c000
	v_add_u32_e32 v162, s58, v145
	v_add_u32_e32 v178, s59, v145
	ds_read_b128 v[150:153], v162
	ds_read_b128 v[154:157], v162 offset:1024
	ds_read_b128 v[158:161], v162 offset:2048
	ds_read_b128 v[162:165], v162 offset:3072
	ds_read_b128 v[166:169], v178
	ds_read_b128 v[170:173], v178 offset:1024
	ds_read_b128 v[174:177], v178 offset:2048
	ds_read_b128 v[178:181], v178 offset:3072
	s_add_u32 s28, s28, 0xb0000
	s_addc_u32 s29, s29, 0
	s_mov_b32 m0, s39
	v_lshl_add_u64 v[224:225], s[28:29], 0, v[128:129]
	ds_read_b128 v[184:187], v149 offset:32768
	ds_read_b128 v[188:191], v149 offset:33792
	ds_read_b128 v[192:195], v149 offset:34816
	ds_read_b128 v[196:199], v149 offset:35840
	ds_read_b128 v[200:203], v149 offset:36864
	ds_read_b128 v[204:207], v149 offset:37888
	ds_read_b128 v[208:211], v149 offset:38912
	ds_read_b128 v[212:215], v149 offset:39936
	global_load_lds_dwordx4 v[224:225], off
	v_lshl_add_u64 v[224:225], s[28:29], 0, v[132:133]
	s_mov_b32 m0, s40
	s_nop 0
	global_load_lds_dwordx4 v[224:225], off
	s_waitcnt vmcnt(8)
	s_waitcnt lgkmcnt(0)
	s_barrier
	s_setprio 1
	v_mfma_f32_16x16x32_bf16 v[124:127], v[150:153], v[184:187], v[124:127]
	v_mfma_f32_16x16x32_bf16 v[120:123], v[158:161], v[184:187], v[120:123]
	v_mfma_f32_16x16x32_bf16 v[116:119], v[150:153], v[192:195], v[116:119]
	v_mfma_f32_16x16x32_bf16 v[112:115], v[158:161], v[192:195], v[112:115]
	v_mfma_f32_16x16x32_bf16 v[100:103], v[150:153], v[200:203], v[100:103]
	v_mfma_f32_16x16x32_bf16 v[96:99], v[158:161], v[200:203], v[96:99]
	v_mfma_f32_16x16x32_bf16 v[84:87], v[150:153], v[208:211], v[84:87]
	v_mfma_f32_16x16x32_bf16 v[80:83], v[158:161], v[208:211], v[80:83]
	v_mfma_f32_16x16x32_bf16 v[124:127], v[154:157], v[188:191], v[124:127]
	v_mfma_f32_16x16x32_bf16 v[120:123], v[162:165], v[188:191], v[120:123]
	v_mfma_f32_16x16x32_bf16 v[116:119], v[154:157], v[196:199], v[116:119]
	v_mfma_f32_16x16x32_bf16 v[112:115], v[162:165], v[196:199], v[112:115]
	v_mfma_f32_16x16x32_bf16 v[100:103], v[154:157], v[204:207], v[100:103]
	v_mfma_f32_16x16x32_bf16 v[96:99], v[162:165], v[204:207], v[96:99]
	v_mfma_f32_16x16x32_bf16 v[84:87], v[154:157], v[212:215], v[84:87]
	v_mfma_f32_16x16x32_bf16 v[80:83], v[162:165], v[212:215], v[80:83]
	v_mfma_f32_16x16x32_bf16 v[108:111], v[166:169], v[184:187], v[108:111]
	v_mfma_f32_16x16x32_bf16 v[104:107], v[174:177], v[184:187], v[104:107]
	v_mfma_f32_16x16x32_bf16 v[92:95], v[166:169], v[192:195], v[92:95]
	v_mfma_f32_16x16x32_bf16 v[88:91], v[174:177], v[192:195], v[88:91]
	v_mfma_f32_16x16x32_bf16 v[76:79], v[166:169], v[200:203], v[76:79]
	v_mfma_f32_16x16x32_bf16 v[72:75], v[174:177], v[200:203], v[72:75]
	v_mfma_f32_16x16x32_bf16 v[68:71], v[166:169], v[208:211], v[68:71]
	v_mfma_f32_16x16x32_bf16 v[64:67], v[174:177], v[208:211], v[64:67]
	v_mfma_f32_16x16x32_bf16 v[108:111], v[170:173], v[188:191], v[108:111]
	v_mfma_f32_16x16x32_bf16 v[104:107], v[178:181], v[188:191], v[104:107]
	v_mfma_f32_16x16x32_bf16 v[92:95], v[170:173], v[196:199], v[92:95]
	v_mfma_f32_16x16x32_bf16 v[88:91], v[178:181], v[196:199], v[88:91]
	v_mfma_f32_16x16x32_bf16 v[76:79], v[170:173], v[204:207], v[76:79]
	v_mfma_f32_16x16x32_bf16 v[72:75], v[178:181], v[204:207], v[72:75]
	v_mfma_f32_16x16x32_bf16 v[68:71], v[170:173], v[212:215], v[68:71]
	v_mfma_f32_16x16x32_bf16 v[64:67], v[178:181], v[212:215], v[64:67]
	s_setprio 0
	s_barrier
	s_add_i32 s28, s58, s36
	v_lshl_add_u64 v[216:217], v[216:217], 0, s[10:11]
	s_mov_b32 m0, s28
	ds_read_b128 v[184:187], v149 offset:49152
	ds_read_b128 v[188:191], v149 offset:50176
	ds_read_b128 v[192:195], v149 offset:51200
	ds_read_b128 v[196:199], v149 offset:52224
	ds_read_b128 v[200:203], v149 offset:53248
	ds_read_b128 v[204:207], v149 offset:54272
	ds_read_b128 v[208:211], v149 offset:55296
	ds_read_b128 v[212:215], v149 offset:56320
	global_load_lds_dwordx4 v[216:217], off
	s_add_i32 m0, s28, 0x2000
	s_add_u32 s26, s26, 0xb0080
	v_lshl_add_u64 v[216:217], v[218:219], 0, s[10:11]
	s_addc_u32 s27, s27, 0
	s_add_i32 s28, s59, s36
	global_load_lds_dwordx4 v[216:217], off
	v_lshl_add_u64 v[216:217], s[26:27], 0, v[130:131]
	s_mov_b32 m0, s28
	s_nop 0
	global_load_lds_dwordx4 v[216:217], off
	v_lshl_add_u64 v[216:217], s[26:27], 0, v[134:135]
	s_add_i32 m0, s28, 0x2000
	s_nop 0
	global_load_lds_dwordx4 v[216:217], off
	v_lshl_add_u64 v[216:217], v[220:221], 0, s[10:11]
	s_mov_b32 m0, s43
	s_nop 0
	global_load_lds_dwordx4 v[216:217], off
	v_lshl_add_u64 v[216:217], v[222:223], 0, s[10:11]
	s_mov_b32 m0, s44
	s_nop 0
	global_load_lds_dwordx4 v[216:217], off
	s_waitcnt vmcnt(8)
	s_waitcnt lgkmcnt(0)
	s_barrier
	s_setprio 1
	v_mfma_f32_16x16x32_bf16 v[60:63], v[150:153], v[184:187], v[60:63]
	v_mfma_f32_16x16x32_bf16 v[56:59], v[158:161], v[184:187], v[56:59]
	v_mfma_f32_16x16x32_bf16 v[52:55], v[150:153], v[192:195], v[52:55]
	v_mfma_f32_16x16x32_bf16 v[48:51], v[158:161], v[192:195], v[48:51]
	v_mfma_f32_16x16x32_bf16 v[36:39], v[150:153], v[200:203], v[36:39]
	v_mfma_f32_16x16x32_bf16 v[32:35], v[158:161], v[200:203], v[32:35]
	v_mfma_f32_16x16x32_bf16 v[20:23], v[150:153], v[208:211], v[20:23]
	v_mfma_f32_16x16x32_bf16 v[16:19], v[158:161], v[208:211], v[16:19]
	v_mfma_f32_16x16x32_bf16 v[60:63], v[154:157], v[188:191], v[60:63]
	v_mfma_f32_16x16x32_bf16 v[56:59], v[162:165], v[188:191], v[56:59]
	v_mfma_f32_16x16x32_bf16 v[52:55], v[154:157], v[196:199], v[52:55]
	v_mfma_f32_16x16x32_bf16 v[48:51], v[162:165], v[196:199], v[48:51]
	v_mfma_f32_16x16x32_bf16 v[36:39], v[154:157], v[204:207], v[36:39]
	v_mfma_f32_16x16x32_bf16 v[32:35], v[162:165], v[204:207], v[32:35]
	v_mfma_f32_16x16x32_bf16 v[20:23], v[154:157], v[212:215], v[20:23]
	v_mfma_f32_16x16x32_bf16 v[16:19], v[162:165], v[212:215], v[16:19]
	v_mfma_f32_16x16x32_bf16 v[44:47], v[166:169], v[184:187], v[44:47]
	v_mfma_f32_16x16x32_bf16 v[40:43], v[174:177], v[184:187], v[40:43]
	v_mfma_f32_16x16x32_bf16 v[28:31], v[166:169], v[192:195], v[28:31]
	v_mfma_f32_16x16x32_bf16 v[24:27], v[174:177], v[192:195], v[24:27]
	v_mfma_f32_16x16x32_bf16 v[12:15], v[166:169], v[200:203], v[12:15]
	v_mfma_f32_16x16x32_bf16 v[8:11], v[174:177], v[200:203], v[8:11]
	v_mfma_f32_16x16x32_bf16 v[4:7], v[166:169], v[208:211], v[4:7]
	v_mfma_f32_16x16x32_bf16 v[0:3], v[174:177], v[208:211], v[0:3]
	v_mfma_f32_16x16x32_bf16 v[44:47], v[170:173], v[188:191], v[44:47]
	v_mfma_f32_16x16x32_bf16 v[40:43], v[178:181], v[188:191], v[40:43]
	v_mfma_f32_16x16x32_bf16 v[28:31], v[170:173], v[196:199], v[28:31]
	v_mfma_f32_16x16x32_bf16 v[24:27], v[178:181], v[196:199], v[24:27]
	v_mfma_f32_16x16x32_bf16 v[12:15], v[170:173], v[204:207], v[12:15]
	v_mfma_f32_16x16x32_bf16 v[8:11], v[178:181], v[204:207], v[8:11]
	v_mfma_f32_16x16x32_bf16 v[4:7], v[170:173], v[212:215], v[4:7]
	v_mfma_f32_16x16x32_bf16 v[0:3], v[178:181], v[212:215], v[0:3]
	s_setprio 0
	s_barrier
	s_add_i32 s57, s57, 2
	s_add_u32 s24, s24, 0x100
	s_addc_u32 s25, s25, 0
	s_add_u32 s55, s55, 0x100
	s_addc_u32 s56, s56, 0
	.p2align	6
